# GEMM LDS tiles: XOR swizzle of 16B chunk for rows 4..11 mod 16 (conflict-free ds_read_b128 fragments), all 13 GEMM copies
# speedup vs baseline: 1.0142x; 1.0076x over previous
; #define G_LOAD(kt_) do { \
;     if constexpr (AF32) { _Pragma("unroll") for (int i = 0; i < 4; ++i) ld16_sc1(ra[i], Af + (size_t)i * 32 * lda + (kt_) * 32); } \
;     else { _Pragma("unroll") for (int i = 0; i < 2; ++i) ld16_sc1(rab[i], Ab + (size_t)i * 64 * lda + (kt_) * 32); } \
;     _Pragma("unroll") for (int i = 0; i < 4; ++i) ld16_sc1(rb[i], Bp + (size_t)(kt_) * bstep + i * 2048); } while (0)
; template <bool AF32, class Epi>
; __device__ __forceinline__ void gemm_tile(unsigned char* smem, const void* Ap, int lda, const bf16_t* WT, int N, int K, const Epi& epi, int m0, int n0,
;                                           GPre& pr, bool preloaded, const void* nAp, int nn0, bool has_next) {
;     ...
;   f32x4 (&ra)[4] = pr.ra; u32x4 (&rab)[2] = pr.rab; u32x4 (&rb)[4] = pr.rb;
;   const int nk = K >> 5;
;   const float* Af = (const float*)Ap + (size_t)(tid >> 3) * lda + (tid & 7) * 4;
;   const bf16_t* Ab = (const bf16_t*)Ap + (size_t)(tid >> 2) * lda + (tid & 3) * 8;
;   const bf16_t* Bp = WT + (size_t)n0 * 32 + tid * 8;
;   const size_t bstep = (size_t)N * 32;
;   const int awf = (tid >> 3) * GLD + (tid & 7) * 4;
;   const int awb = (tid >> 2) * GLD + (tid & 3) * 8;
;     ...
;   if (!preloaded) G_LOAD(0);
; __device__ __forceinline__ void run_phase(int ph, KParams kp, unsigned char* smem) {
;     ...
;           int u = t - n_ab; const int l = u / n_kv; u -= l * n_kv; const int mt = u >> 3, nt = u & 7;
;           EpiStore<true> e{(bf16_t*)(ws + WS_KVMEM) + (size_t)l * 4608 * 2048, 2048};
;           gemm_tile<true>(smem, mem_row(kp->mem_prompt, kp->mem_sample, mt * 128), 1024, (const bf16_t*)(ws + WS_WT_KV) + (size_t)l * 2048 * 1024, 2048, 1024, e, mt * 128, nt * 256, pr, false, nullptr, 0, false);
.LBB0_124:
	s_cmpk_gt_i32 s77, 0x17ff
	s_mov_b64 s[0:1], -1
	s_cbranch_scc0 .LBB0_136
	s_add_i32 s2, s77, 0xffffe800
	s_cmpk_gt_u32 s2, 0x11f
	s_cselect_b64 s[0:1], -1, 0
	s_and_b64 s[4:5], s[0:1], exec
	s_cselect_b32 s3, 0xfffffee0, 0
	s_add_i32 s3, s3, s2
	s_load_dwordx4 s[4:7], s[16:17], 0x10
	s_lshl_b32 s2, s3, 4
	s_and_b32 s2, s2, 0xffffff80
	s_add_i32 s3, s2, 0xfffff000
	s_ashr_i32 s8, s2, 31
	s_cmpk_lt_i32 s2, 0x1000
	s_cselect_b32 s9, s8, 0
	s_cselect_b32 s8, s2, s3
	s_waitcnt lgkmcnt(0)
	s_cselect_b32 s5, s5, s7
	s_cselect_b32 s4, s4, s6
	s_lshl_b64 s[6:7], s[8:9], 12
	s_add_u32 s14, s4, s6
	s_addc_u32 s15, s5, s7
	s_and_b64 s[8:9], s[0:1], exec
	v_mov_b32_e32 v2, v210
	s_cselect_b32 s3, 0x400000, 0
	s_add_u32 s9, s66, s3
	v_ashrrev_i32_e32 v162, 3, v2
	v_ashrrev_i32_e32 v163, 31, v162
	s_addc_u32 s13, s67, 0
	s_lshl_b32 s8, s77, 8
	v_lshlrev_b64 v[44:45], 12, v[162:163]
	v_and_b32_e32 v163, 7, v2
	s_and_b32 s8, s8, 0x700
	v_lshl_add_u64 v[0:1], s[14:15], 0, v[44:45]
	v_lshlrev_b32_e32 v46, 4, v163
	v_mov_b32_e32 v47, v161
	v_lshl_add_u64 v[32:33], v[0:1], 0, v[46:47]
	v_lshlrev_b32_e32 v0, 3, v2
	s_lshl_b32 s33, s8, 6
	s_add_u32 s14, s9, s33
	v_ashrrev_i32_e32 v1, 31, v0
	v_readfirstlane_b32 s24, v2
	v_and_b32_e32 v54, 15, v2
	v_bfe_u32 v55, v2, 4, 2
	v_lshrrev_b32_e32 v3, 2, v2
	v_and_b32_e32 v2, 24, v0
	s_addc_u32 s15, s13, 0
	v_lshlrev_b64 v[52:53], 1, v[0:1]
	v_mul_lo_u32 v0, v162, 40
	v_lshl_add_u64 v[48:49], s[14:15], 0, v[52:53]
	v_lshl_add_u32 v181, v163, 2, v0
	v_lshrrev_b32_e32 v250, 3, v210
	v_add_u32_e32 v251, 4, v250
	v_and_b32_e32 v251, 8, v251
	v_and_b32_e32 v252, 7, v210
	v_lshlrev_b32_e32 v252, 2, v252
	v_xor_b32_e32 v252, v252, v251
	v_mad_u32_u24 v181, v250, 40, v252
	v_mad_u64_u32 v[170:171], s[14:15], v3, 40, v[2:3]
	v_lshrrev_b32_e32 v250, 2, v210
	v_add_u32_e32 v251, 4, v250
	v_and_b32_e32 v251, 8, v251
	v_and_b32_e32 v252, 3, v210
	v_lshlrev_b32_e32 v252, 3, v252
	v_xor_b32_e32 v252, v252, v251
	v_mad_u32_u24 v170, v250, 40, v252
	global_load_dwordx4 v[0:3], v[32:33], off sc1
	v_lshl_add_u64 v[4:5], v[32:33], 0, s[26:27]
	global_load_dwordx4 v[4:7], v[4:5], off sc1
	v_lshl_add_u64 v[8:9], v[32:33], 0, s[28:29]
	global_load_dwordx4 v[8:11], v[8:9], off sc1
	v_lshl_add_u64 v[12:13], v[32:33], 0, s[22:23]
	global_load_dwordx4 v[12:15], v[12:13], off sc1
	global_load_dwordx4 v[16:19], v[48:49], off sc1
	v_lshl_add_u64 v[20:21], v[48:49], 0, s[30:31]
	global_load_dwordx4 v[20:23], v[20:21], off sc1
	v_lshl_add_u64 v[24:25], v[48:49], 0, s[34:35]
	global_load_dwordx4 v[24:27], v[24:25], off sc1
	v_lshl_add_u64 v[28:29], v[48:49], 0, s[36:37]
	global_load_dwordx4 v[28:31], v[28:29], off sc1
	v_lshlrev_b32_e32 v171, 1, v181
	s_waitcnt vmcnt(0)
; #define G_LOAD(kt_) do { \
;     if constexpr (AF32) { _Pragma("unroll") for (int i = 0; i < 4; ++i) ld16_sc1(ra[i], Af + (size_t)i * 32 * lda + (kt_) * 32); } \
;     else { _Pragma("unroll") for (int i = 0; i < 2; ++i) ld16_sc1(rab[i], Ab + (size_t)i * 64 * lda + (kt_) * 32); } \
;     _Pragma("unroll") for (int i = 0; i < 4; ++i) ld16_sc1(rb[i], Bp + (size_t)(kt_) * bstep + i * 2048); } while (0)
; template <bool AF32, class Epi>
; __device__ __forceinline__ void gemm_tile(unsigned char* smem, const void* Ap, int lda, const bf16_t* WT, int N, int K, const Epi& epi, int m0, int n0,
;                                           GPre& pr, bool preloaded, const void* nAp, int nn0, bool has_next) {
;     ...
;   f32x4 acc[4][8];
; #pragma unroll
;   for (int m = 0; m < 4; ++m)
; #pragma unroll
;     for (int n = 0; n < 8; ++n) acc[m][n] = (f32x4){0.f, 0.f, 0.f, 0.f};
;   float ss[4];
; #pragma unroll
;   for (int i = 0; i < 4; ++i) ss[i] = 0.f;
;   f32x4 (&ra)[4] = pr.ra; u32x4 (&rab)[2] = pr.rab; u32x4 (&rb)[4] = pr.rb;
;   const int nk = K >> 5;
;   const float* Af = (const float*)Ap + (size_t)(tid >> 3) * lda + (tid & 7) * 4;
;   const bf16_t* Ab = (const bf16_t*)Ap + (size_t)(tid >> 2) * lda + (tid & 3) * 8;
;   const bf16_t* Bp = WT + (size_t)n0 * 32 + tid * 8;
;   const size_t bstep = (size_t)N * 32;
;   const int awf = (tid >> 3) * GLD + (tid & 7) * 4;
;   const int awb = (tid >> 2) * GLD + (tid & 3) * 8;
;     ...
;   if (!preloaded) G_LOAD(0);
;   G_STORE(0);
;   if (nk > 1) G_LOAD(1);
;   __syncthreads();
;   for (int kt = 0; kt < nk; ++kt) {
;     const int cur = kt & 1;
;     if (kt + 1 < nk) G_STORE(cur ^ 1);
;     if (kt + 2 < nk) G_LOAD(kt + 2);
;     const bf16_t* a_s = sbase + cur * G_STAGE + (wr * 64 + l15) * GLD + quad * 8;
;     const bf16_t* b_s = sbase + cur * G_STAGE + 128 * GLD + (wc * 128 + l15) * GLD + quad * 8;
	v_lshlrev_b32_e32 v182, 1, v170
	v_cvt_pk_bf16_f32 v34, v0, v1
	v_mov_b32_e32 v37, v0
	v_mov_b32_e32 v0, v5
	v_mov_b32_e32 v36, v4
	v_pk_mul_f32 v[0:1], v[0:1], v[0:1]
	v_cvt_pk_bf16_f32 v35, v2, v3
	v_pk_fma_f32 v[0:1], v[36:37], v[36:37], v[0:1]
	v_mov_b32_e32 v36, v6
	v_mov_b32_e32 v37, v2
	v_pk_fma_f32 v[0:1], v[36:37], v[36:37], v[0:1]
	v_mov_b32_e32 v2, v7
	v_pk_fma_f32 v[168:169], v[2:3], v[2:3], v[0:1]
	v_cvt_pk_bf16_f32 v0, v4, v5
	v_cvt_pk_bf16_f32 v1, v6, v7
	ds_write2st64_b64 v171, v[34:35], v[0:1] offset1:5
	v_cvt_pk_bf16_f32 v0, v8, v9
	v_mov_b32_e32 v3, v8
	v_mov_b32_e32 v8, v13
	v_mov_b32_e32 v2, v12
	v_pk_mul_f32 v[4:5], v[8:9], v[8:9]
	v_cvt_pk_bf16_f32 v1, v10, v11
	v_pk_fma_f32 v[2:3], v[2:3], v[2:3], v[4:5]
	v_mov_b32_e32 v4, v14
	v_mov_b32_e32 v5, v10
	v_pk_fma_f32 v[2:3], v[4:5], v[4:5], v[2:3]
	v_mov_b32_e32 v10, v15
	v_pk_fma_f32 v[164:165], v[10:11], v[10:11], v[2:3]
	v_cvt_pk_bf16_f32 v2, v12, v13
	v_cvt_pk_bf16_f32 v3, v14, v15
	ds_write2st64_b64 v171, v[0:1], v[2:3] offset0:10 offset1:15
	ds_write_b128 v182, v[16:19] offset:10240
	ds_write_b128 v182, v[20:23] offset:15360
	ds_write_b128 v182, v[24:27] offset:20480
	ds_write_b128 v182, v[28:31] offset:25600
	v_lshl_add_u64 v[0:1], v[32:33], 0, s[38:39]
	global_load_dwordx4 v[16:19], v[0:1], off sc1
	v_lshl_add_u64 v[0:1], v[32:33], 0, s[42:43]
	global_load_dwordx4 v[8:11], v[0:1], off sc1
	v_lshl_add_u64 v[0:1], v[32:33], 0, s[44:45]
	global_load_dwordx4 v[4:7], v[0:1], off sc1
	v_lshl_add_u64 v[0:1], v[32:33], 0, s[46:47]
	global_load_dwordx4 v[0:3], v[0:1], off sc1
	v_lshl_add_u64 v[12:13], v[48:49], 0, s[26:27]
	s_ashr_i32 s9, s24, 1
	global_load_dwordx4 v[32:35], v[12:13], off sc1
	v_lshl_add_u64 v[12:13], v[48:49], 0, s[48:49]
	s_andn2_b32 s9, s9, 63
	global_load_dwordx4 v[36:39], v[12:13], off sc1
	v_lshl_add_u64 v[12:13], v[48:49], 0, s[50:51]
	v_or_b32_e32 v167, s9, v54
	s_lshl_b32 s9, s24, 1
	global_load_dwordx4 v[40:43], v[12:13], off sc1
	v_lshl_add_u64 v[12:13], v[48:49], 0, s[52:53]
	s_and_b32 s9, s9, 0x80
	global_load_dwordx4 v[48:51], v[12:13], off sc1
	v_or_b32_e32 v12, s9, v54
	v_mul_u32_u24_e32 v183, 0x50, v12
	v_lshl_add_u64 v[12:13], s[6:7], 0, v[44:45]
	s_or_b32 s3, s3, s33
	v_or_b32_e32 v12, v12, v46
	s_add_u32 s14, s68, s3
	v_lshl_add_u64 v[12:13], s[4:5], 0, v[12:13]
	v_lshlrev_b32_e32 v160, 3, v55
	s_addc_u32 s15, s69, 0
	v_lshl_add_u64 v[174:175], v[12:13], 0, s[54:55]
	v_mov_b32_e32 v12, 0
	s_mov_b32 s12, 0
	v_mul_lo_u32 v166, v167, s72
	v_lshl_add_u64 v[172:173], s[14:15], 0, v[52:53]
	v_lshlrev_b32_e32 v184, 1, v160
	v_add_u32_e32 v250, 4, v210
	v_and_b32_e32 v250, 8, v250
	v_lshlrev_b32_e32 v250, 1, v250
	v_xor_b32_e32 v184, v184, v250
	v_mov_b32_e32 v13, v12
	v_mov_b32_e32 v14, v12
	v_mov_b32_e32 v15, v12
	v_mov_b32_e32 v20, v12
	v_mov_b32_e32 v21, v12
	v_mov_b32_e32 v22, v12
	v_mov_b32_e32 v23, v12
	v_mov_b32_e32 v24, v12
	v_mov_b32_e32 v25, v12
	v_mov_b32_e32 v26, v12
	v_mov_b32_e32 v27, v12
	v_mov_b32_e32 v28, v12
	v_mov_b32_e32 v29, v12
	v_mov_b32_e32 v30, v12
	v_mov_b32_e32 v31, v12
	v_mov_b32_e32 v52, v12
	v_mov_b32_e32 v53, v12
	v_mov_b32_e32 v54, v12
	v_mov_b32_e32 v55, v12
	v_mov_b32_e32 v60, v12
	v_mov_b32_e32 v61, v12
	v_mov_b32_e32 v62, v12
	v_mov_b32_e32 v63, v12
	v_mov_b32_e32 v68, v12
	v_mov_b32_e32 v69, v12
	v_mov_b32_e32 v70, v12
	v_mov_b32_e32 v71, v12
	v_mov_b32_e32 v76, v12
	v_mov_b32_e32 v77, v12
	v_mov_b32_e32 v78, v12
	v_mov_b32_e32 v79, v12
	v_mov_b32_e32 v44, v12
	v_mov_b32_e32 v45, v12
	v_mov_b32_e32 v46, v12
	v_mov_b32_e32 v47, v12
	v_mov_b32_e32 v56, v12
	v_mov_b32_e32 v57, v12
	v_mov_b32_e32 v58, v12
	v_mov_b32_e32 v59, v12
	v_mov_b32_e32 v64, v12
	v_mov_b32_e32 v65, v12
	v_mov_b32_e32 v66, v12
	v_mov_b32_e32 v67, v12
	v_mov_b32_e32 v72, v12
	v_mov_b32_e32 v73, v12
	v_mov_b32_e32 v74, v12
	v_mov_b32_e32 v75, v12
	v_mov_b32_e32 v84, v12
	v_mov_b32_e32 v85, v12
	v_mov_b32_e32 v86, v12
	v_mov_b32_e32 v87, v12
	v_mov_b32_e32 v92, v12
	v_mov_b32_e32 v93, v12
	v_mov_b32_e32 v94, v12
	v_mov_b32_e32 v95, v12
	v_mov_b32_e32 v100, v12
	v_mov_b32_e32 v101, v12
	v_mov_b32_e32 v102, v12
	v_mov_b32_e32 v103, v12
	v_mov_b32_e32 v108, v12
	v_mov_b32_e32 v109, v12
	v_mov_b32_e32 v110, v12
	v_mov_b32_e32 v111, v12
	v_mov_b32_e32 v80, v12
	v_mov_b32_e32 v81, v12
	v_mov_b32_e32 v82, v12
	v_mov_b32_e32 v83, v12
	v_mov_b32_e32 v88, v12
	v_mov_b32_e32 v89, v12
	v_mov_b32_e32 v90, v12
	v_mov_b32_e32 v91, v12
	v_mov_b32_e32 v96, v12
	v_mov_b32_e32 v97, v12
	v_mov_b32_e32 v98, v12
	v_mov_b32_e32 v99, v12
	v_mov_b32_e32 v104, v12
	v_mov_b32_e32 v105, v12
	v_mov_b32_e32 v106, v12
	v_mov_b32_e32 v107, v12
	v_mov_b32_e32 v116, v12
	v_mov_b32_e32 v117, v12
	v_mov_b32_e32 v118, v12
	v_mov_b32_e32 v119, v12
	v_mov_b32_e32 v124, v12
	v_mov_b32_e32 v125, v12
	v_mov_b32_e32 v126, v12
	v_mov_b32_e32 v127, v12
	v_mov_b32_e32 v136, v12
	v_mov_b32_e32 v137, v12
	v_mov_b32_e32 v138, v12
	v_mov_b32_e32 v139, v12
	v_mov_b32_e32 v140, v12
	v_mov_b32_e32 v141, v12
	v_mov_b32_e32 v142, v12
	v_mov_b32_e32 v143, v12
	v_mov_b32_e32 v112, v12
	v_mov_b32_e32 v113, v12
	v_mov_b32_e32 v114, v12
	v_mov_b32_e32 v115, v12
	v_mov_b32_e32 v120, v12
	v_mov_b32_e32 v121, v12
	v_mov_b32_e32 v122, v12
	v_mov_b32_e32 v123, v12
	v_mov_b32_e32 v128, v12
	v_mov_b32_e32 v129, v12
	v_mov_b32_e32 v130, v12
	v_mov_b32_e32 v131, v12
	v_mov_b32_e32 v132, v12
	v_mov_b32_e32 v133, v12
	v_mov_b32_e32 v134, v12
	v_mov_b32_e32 v135, v12
	v_mov_b32_e32 v144, v12
	v_mov_b32_e32 v145, v12
	v_mov_b32_e32 v146, v12
	v_mov_b32_e32 v147, v12
	v_mov_b32_e32 v148, v12
	v_mov_b32_e32 v149, v12
	v_mov_b32_e32 v150, v12
	v_mov_b32_e32 v151, v12
	v_mov_b32_e32 v152, v12
	v_mov_b32_e32 v153, v12
	v_mov_b32_e32 v154, v12
	v_mov_b32_e32 v155, v12
	v_mov_b32_e32 v156, v12
	v_mov_b32_e32 v157, v12
	v_mov_b32_e32 v158, v12
	v_mov_b32_e32 v159, v12
	s_waitcnt lgkmcnt(0)
	s_barrier

; #define G_LOAD(kt_) do { \
;     if constexpr (AF32) { _Pragma("unroll") for (int i = 0; i < 4; ++i) ld16_sc1(ra[i], Af + (size_t)i * 32 * lda + (kt_) * 32); } \
;     else { _Pragma("unroll") for (int i = 0; i < 2; ++i) ld16_sc1(rab[i], Ab + (size_t)i * 64 * lda + (kt_) * 32); } \
;     _Pragma("unroll") for (int i = 0; i < 4; ++i) ld16_sc1(rb[i], Bp + (size_t)(kt_) * bstep + i * 2048); } while (0)
; template <bool AF32, class Epi>
; __device__ __forceinline__ void gemm_tile(unsigned char* smem, const void* Ap, int lda, const bf16_t* WT, int N, int K, const Epi& epi, int m0, int n0,
;                                           GPre& pr, bool preloaded, const void* nAp, int nn0, bool has_next) {
;     ...
;   const float* Af = (const float*)Ap + (size_t)(tid >> 3) * lda + (tid & 7) * 4;
;   const bf16_t* Ab = (const bf16_t*)Ap + (size_t)(tid >> 2) * lda + (tid & 3) * 8;
;   const bf16_t* Bp = WT + (size_t)n0 * 32 + tid * 8;
;   const size_t bstep = (size_t)N * 32;
;   const int awf = (tid >> 3) * GLD + (tid & 7) * 4;
;   const int awb = (tid >> 2) * GLD + (tid & 3) * 8;
;     ...
;   if (!preloaded) G_LOAD(0);
; __device__ __forceinline__ void run_phase(int ph, KParams kp, unsigned char* smem) {
;     ...
;           int mt, nt; tile_map(t, 12, gridDim.x, mt, nt);
;           EpiInAB e{Z, kp->g_qn, kp->g_kn, (const float2*)(ws + WS_ROPE)};
;           gemm_tile<true>(smem, xin_row(kp->x_prompt, kp->x_sample, mt * 128), 1024, (const bf16_t*)(ws + WS_WT_IN_AB), 3072, 1024, e, mt * 128, nt * 256, pr, false, nullptr, 0, false);
.LBB0_140:
	s_load_dwordx4 s[80:83], s[16:17], 0x0
	s_load_dwordx4 s[12:15], s[16:17], 0x30
	s_lshl_b32 s2, s4, 7
	s_add_i32 s0, s2, 0xffff8000
	s_ashr_i32 s1, s2, 31
	s_cmpk_lt_i32 s4, 0x100
	s_cselect_b32 s1, s1, 0
	s_cselect_b32 s0, s2, s0
	v_mov_b32_e32 v2, v210
	s_waitcnt lgkmcnt(0)
	s_cselect_b32 s5, s81, s83
	s_cselect_b32 s4, s80, s82
	s_lshl_b64 s[6:7], s[0:1], 12
	s_add_u32 s78, s4, s6
	v_ashrrev_i32_e32 v164, 3, v2
	v_ashrrev_i32_e32 v165, 31, v164
	s_addc_u32 s79, s5, s7
	v_lshlrev_b64 v[32:33], 12, v[164:165]
	v_and_b32_e32 v165, 7, v2
	s_lshl_b32 s0, s8, 8
	v_lshl_add_u64 v[0:1], s[78:79], 0, v[32:33]
	v_lshlrev_b32_e32 v160, 4, v165
	v_lshl_add_u64 v[34:35], v[0:1], 0, v[160:161]
	s_ashr_i32 s1, s0, 31
	v_readfirstlane_b32 s3, v2
	v_and_b32_e32 v181, 15, v2
	v_bfe_u32 v182, v2, 4, 2
	v_lshrrev_b32_e32 v46, 2, v2
	v_lshlrev_b32_e32 v36, 3, v2
	s_lshl_b64 s[8:9], s[0:1], 6
	global_load_dwordx4 v[0:3], v[34:35], off sc1
	v_lshl_add_u64 v[4:5], v[34:35], 0, s[26:27]
	v_ashrrev_i32_e32 v37, 31, v36
	global_load_dwordx4 v[4:7], v[4:5], off sc1
	v_lshl_add_u64 v[8:9], v[34:35], 0, s[28:29]
	s_add_u32 s78, s10, s8
	global_load_dwordx4 v[8:11], v[8:9], off sc1
	v_lshl_add_u64 v[12:13], v[34:35], 0, s[22:23]
	s_addc_u32 s79, s11, s9
	v_lshlrev_b64 v[40:41], 1, v[36:37]
	v_mul_lo_u32 v16, v164, 40
	global_load_dwordx4 v[12:15], v[12:13], off sc1
	v_lshl_add_u64 v[38:39], s[78:79], 0, v[40:41]
	v_lshl_add_u32 v184, v165, 2, v16
	v_lshrrev_b32_e32 v250, 3, v210
	v_add_u32_e32 v251, 4, v250
	v_and_b32_e32 v251, 8, v251
	v_and_b32_e32 v252, 7, v210
	v_lshlrev_b32_e32 v252, 2, v252
	v_xor_b32_e32 v252, v252, v251
	v_mad_u32_u24 v184, v250, 40, v252
	global_load_dwordx4 v[16:19], v[38:39], off sc1
	v_lshl_add_u64 v[20:21], v[38:39], 0, s[30:31]
	global_load_dwordx4 v[20:23], v[20:21], off sc1
	v_lshl_add_u64 v[24:25], v[38:39], 0, s[34:35]
	global_load_dwordx4 v[24:27], v[24:25], off sc1
	v_lshl_add_u64 v[28:29], v[38:39], 0, s[36:37]
	global_load_dwordx4 v[28:31], v[28:29], off sc1
	v_lshlrev_b32_e32 v183, 1, v184
	s_waitcnt vmcnt(0)
; #define G_LOAD(kt_) do { \
;     if constexpr (AF32) { _Pragma("unroll") for (int i = 0; i < 4; ++i) ld16_sc1(ra[i], Af + (size_t)i * 32 * lda + (kt_) * 32); } \
;     else { _Pragma("unroll") for (int i = 0; i < 2; ++i) ld16_sc1(rab[i], Ab + (size_t)i * 64 * lda + (kt_) * 32); } \
;     _Pragma("unroll") for (int i = 0; i < 4; ++i) ld16_sc1(rb[i], Bp + (size_t)(kt_) * bstep + i * 2048); } while (0)
; template <bool AF32, class Epi>
; __device__ __forceinline__ void gemm_tile(unsigned char* smem, const void* Ap, int lda, const bf16_t* WT, int N, int K, const Epi& epi, int m0, int n0,
;                                           GPre& pr, bool preloaded, const void* nAp, int nn0, bool has_next) {
;     ...
;   f32x4 acc[4][8];
; #pragma unroll
;   for (int m = 0; m < 4; ++m)
; #pragma unroll
;     for (int n = 0; n < 8; ++n) acc[m][n] = (f32x4){0.f, 0.f, 0.f, 0.f};
;   float ss[4];
; #pragma unroll
;   for (int i = 0; i < 4; ++i) ss[i] = 0.f;
;   f32x4 (&ra)[4] = pr.ra; u32x4 (&rab)[2] = pr.rab; u32x4 (&rb)[4] = pr.rb;
;   const int nk = K >> 5;
;   const float* Af = (const float*)Ap + (size_t)(tid >> 3) * lda + (tid & 7) * 4;
;   const bf16_t* Ab = (const bf16_t*)Ap + (size_t)(tid >> 2) * lda + (tid & 3) * 8;
;   const bf16_t* Bp = WT + (size_t)n0 * 32 + tid * 8;
;   const size_t bstep = (size_t)N * 32;
;   const int awf = (tid >> 3) * GLD + (tid & 7) * 4;
;   const int awb = (tid >> 2) * GLD + (tid & 3) * 8;
;     ...
;   if (!preloaded) G_LOAD(0);
;   G_STORE(0);
;   if (nk > 1) G_LOAD(1);
;   __syncthreads();
;   for (int kt = 0; kt < nk; ++kt) {
;     const int cur = kt & 1;
;     if (kt + 1 < nk) G_STORE(cur ^ 1);
;     if (kt + 2 < nk) G_LOAD(kt + 2);
;     const bf16_t* a_s = sbase + cur * G_STAGE + (wr * 64 + l15) * GLD + quad * 8;
;     const bf16_t* b_s = sbase + cur * G_STAGE + 128 * GLD + (wc * 128 + l15) * GLD + quad * 8;
	v_and_b32_e32 v36, 24, v36
	v_cvt_pk_bf16_f32 v42, v0, v1
	v_mov_b32_e32 v45, v0
	v_mov_b32_e32 v0, v5
	v_mov_b32_e32 v44, v4
	v_pk_mul_f32 v[0:1], v[0:1], v[0:1]
	v_cvt_pk_bf16_f32 v43, v2, v3
	v_pk_fma_f32 v[0:1], v[44:45], v[44:45], v[0:1]
	v_mov_b32_e32 v44, v6
	v_mov_b32_e32 v45, v2
	v_pk_fma_f32 v[0:1], v[44:45], v[44:45], v[0:1]
	v_mov_b32_e32 v2, v7
	v_pk_fma_f32 v[168:169], v[2:3], v[2:3], v[0:1]
	v_cvt_pk_bf16_f32 v0, v4, v5
	v_cvt_pk_bf16_f32 v1, v6, v7
	ds_write2st64_b64 v183, v[42:43], v[0:1] offset1:5
	v_cvt_pk_bf16_f32 v0, v8, v9
	v_mov_b32_e32 v3, v8
	v_mov_b32_e32 v8, v13
	v_mov_b32_e32 v2, v12
	v_pk_mul_f32 v[4:5], v[8:9], v[8:9]
	v_cvt_pk_bf16_f32 v1, v10, v11
	v_pk_fma_f32 v[2:3], v[2:3], v[2:3], v[4:5]
	v_mov_b32_e32 v4, v14
	v_mov_b32_e32 v5, v10
	v_pk_fma_f32 v[2:3], v[4:5], v[4:5], v[2:3]
	v_mov_b32_e32 v10, v15
	v_mad_u64_u32 v[170:171], s[78:79], v46, 40, v[36:37]
	v_lshrrev_b32_e32 v250, 2, v210
	v_add_u32_e32 v251, 4, v250
	v_and_b32_e32 v251, 8, v251
	v_and_b32_e32 v252, 3, v210
	v_lshlrev_b32_e32 v252, 3, v252
	v_xor_b32_e32 v252, v252, v251
	v_mad_u32_u24 v170, v250, 40, v252
	v_pk_fma_f32 v[166:167], v[10:11], v[10:11], v[2:3]
	v_cvt_pk_bf16_f32 v2, v12, v13
	v_cvt_pk_bf16_f32 v3, v14, v15
	v_lshlrev_b32_e32 v171, 1, v170
	ds_write2st64_b64 v183, v[0:1], v[2:3] offset0:10 offset1:15
	ds_write_b128 v171, v[16:19] offset:10240
	ds_write_b128 v171, v[20:23] offset:15360
	ds_write_b128 v171, v[24:27] offset:20480
	ds_write_b128 v171, v[28:31] offset:25600
	v_lshl_add_u64 v[0:1], v[34:35], 0, s[38:39]
	global_load_dwordx4 v[4:7], v[0:1], off sc1
	v_lshl_add_u64 v[0:1], v[34:35], 0, s[42:43]
	global_load_dwordx4 v[136:139], v[0:1], off sc1
	v_lshl_add_u64 v[0:1], v[34:35], 0, s[44:45]
	global_load_dwordx4 v[132:135], v[0:1], off sc1
	v_lshl_add_u64 v[0:1], v[34:35], 0, s[46:47]
	global_load_dwordx4 v[128:131], v[0:1], off sc1
	v_lshl_add_u64 v[0:1], v[38:39], 0, s[56:57]
	s_ashr_i32 s1, s3, 1
	global_load_dwordx4 v[20:23], v[0:1], off sc1
	v_lshl_add_u64 v[0:1], v[38:39], 0, s[58:59]
	s_andn2_b32 s1, s1, 63
	global_load_dwordx4 v[24:27], v[0:1], off sc1
	v_lshl_add_u64 v[0:1], v[38:39], 0, s[60:61]
	v_or_b32_e32 v163, s1, v181
	s_lshl_b32 s1, s3, 1
	global_load_dwordx4 v[28:31], v[0:1], off sc1
	v_lshl_add_u64 v[0:1], v[38:39], 0, s[62:63]
	s_and_b32 s1, s1, 0x80
	global_load_dwordx4 v[36:39], v[0:1], off sc1
	v_or_b32_e32 v0, s1, v181
	v_mul_u32_u24_e32 v185, 0x50, v0
	v_lshl_add_u64 v[0:1], s[6:7], 0, v[32:33]
	v_or_b32_e32 v0, v0, v160
	s_add_u32 s8, s70, s8
	v_lshl_add_u64 v[0:1], s[4:5], 0, v[0:1]
	v_lshlrev_b32_e32 v2, 3, v182
	s_addc_u32 s9, s71, s9
	v_lshl_add_u64 v[174:175], v[0:1], 0, s[54:55]
	v_mov_b32_e32 v0, 0
	v_mul_lo_u32 v162, v163, s72
	v_lshl_add_u64 v[172:173], s[8:9], 0, v[40:41]
	s_mov_b32 s4, 0
	v_lshlrev_b32_e32 v160, 1, v2
	v_add_u32_e32 v250, 4, v210
	v_and_b32_e32 v250, 8, v250
	v_lshlrev_b32_e32 v250, 1, v250
	v_xor_b32_e32 v160, v160, v250
	v_mov_b32_e32 v1, v0
	v_mov_b32_e32 v2, v0
	v_mov_b32_e32 v3, v0
	v_mov_b32_e32 v8, v0
	v_mov_b32_e32 v9, v0
	v_mov_b32_e32 v10, v0
	v_mov_b32_e32 v11, v0
	v_mov_b32_e32 v12, v0
	v_mov_b32_e32 v13, v0
	v_mov_b32_e32 v14, v0
	v_mov_b32_e32 v15, v0
	v_mov_b32_e32 v16, v0
	v_mov_b32_e32 v17, v0
	v_mov_b32_e32 v18, v0
	v_mov_b32_e32 v19, v0
	v_mov_b32_e32 v40, v0
	v_mov_b32_e32 v41, v0
	v_mov_b32_e32 v42, v0
	v_mov_b32_e32 v43, v0
	v_mov_b32_e32 v48, v0
	v_mov_b32_e32 v49, v0
	v_mov_b32_e32 v50, v0
	v_mov_b32_e32 v51, v0
	v_mov_b32_e32 v56, v0
	v_mov_b32_e32 v57, v0
	v_mov_b32_e32 v58, v0
	v_mov_b32_e32 v59, v0
	v_mov_b32_e32 v64, v0
	v_mov_b32_e32 v65, v0
	v_mov_b32_e32 v66, v0
	v_mov_b32_e32 v67, v0
	v_mov_b32_e32 v32, v0
	v_mov_b32_e32 v33, v0
	v_mov_b32_e32 v34, v0
	v_mov_b32_e32 v35, v0
	v_mov_b32_e32 v44, v0
	v_mov_b32_e32 v45, v0
	v_mov_b32_e32 v46, v0
	v_mov_b32_e32 v47, v0
	v_mov_b32_e32 v52, v0
	v_mov_b32_e32 v53, v0
	v_mov_b32_e32 v54, v0
	v_mov_b32_e32 v55, v0
	v_mov_b32_e32 v60, v0
	v_mov_b32_e32 v61, v0
	v_mov_b32_e32 v62, v0
	v_mov_b32_e32 v63, v0
	v_mov_b32_e32 v72, v0
	v_mov_b32_e32 v73, v0
	v_mov_b32_e32 v74, v0
	v_mov_b32_e32 v75, v0
	v_mov_b32_e32 v80, v0
	v_mov_b32_e32 v81, v0
	v_mov_b32_e32 v82, v0
	v_mov_b32_e32 v83, v0
	v_mov_b32_e32 v88, v0
	v_mov_b32_e32 v89, v0
	v_mov_b32_e32 v90, v0
	v_mov_b32_e32 v91, v0
	v_mov_b32_e32 v96, v0
	v_mov_b32_e32 v97, v0
	v_mov_b32_e32 v98, v0
	v_mov_b32_e32 v99, v0
	v_mov_b32_e32 v68, v0
	v_mov_b32_e32 v69, v0
	v_mov_b32_e32 v70, v0
	v_mov_b32_e32 v71, v0
	v_mov_b32_e32 v76, v0
	v_mov_b32_e32 v77, v0
	v_mov_b32_e32 v78, v0
	v_mov_b32_e32 v79, v0
	v_mov_b32_e32 v84, v0
	v_mov_b32_e32 v85, v0
	v_mov_b32_e32 v86, v0
	v_mov_b32_e32 v87, v0
	v_mov_b32_e32 v92, v0
	v_mov_b32_e32 v93, v0
	v_mov_b32_e32 v94, v0
	v_mov_b32_e32 v95, v0
	v_mov_b32_e32 v104, v0
	v_mov_b32_e32 v105, v0
	v_mov_b32_e32 v106, v0
	v_mov_b32_e32 v107, v0
	v_mov_b32_e32 v112, v0
	v_mov_b32_e32 v113, v0
	v_mov_b32_e32 v114, v0
	v_mov_b32_e32 v115, v0
	v_mov_b32_e32 v124, v0
	v_mov_b32_e32 v125, v0
	v_mov_b32_e32 v126, v0
	v_mov_b32_e32 v127, v0
	v_mov_b32_e32 v140, v0
	v_mov_b32_e32 v141, v0
	v_mov_b32_e32 v142, v0
	v_mov_b32_e32 v143, v0
	v_mov_b32_e32 v100, v0
	v_mov_b32_e32 v101, v0
	v_mov_b32_e32 v102, v0
	v_mov_b32_e32 v103, v0
	v_mov_b32_e32 v108, v0
	v_mov_b32_e32 v109, v0
	v_mov_b32_e32 v110, v0
	v_mov_b32_e32 v111, v0
	v_mov_b32_e32 v116, v0
	v_mov_b32_e32 v117, v0
	v_mov_b32_e32 v118, v0
	v_mov_b32_e32 v119, v0
	v_mov_b32_e32 v120, v0
	v_mov_b32_e32 v121, v0
	v_mov_b32_e32 v122, v0
	v_mov_b32_e32 v123, v0
	v_mov_b32_e32 v144, v0
	v_mov_b32_e32 v145, v0
	v_mov_b32_e32 v146, v0
	v_mov_b32_e32 v147, v0
	v_mov_b32_e32 v148, v0
	v_mov_b32_e32 v149, v0
	v_mov_b32_e32 v150, v0
	v_mov_b32_e32 v151, v0
	v_mov_b32_e32 v152, v0
	v_mov_b32_e32 v153, v0
	v_mov_b32_e32 v154, v0
	v_mov_b32_e32 v155, v0
	v_mov_b32_e32 v156, v0
	v_mov_b32_e32 v157, v0
	v_mov_b32_e32 v158, v0
	v_mov_b32_e32 v159, v0
	s_waitcnt lgkmcnt(0)
	s_barrier

; #define G_LOAD(kt_) do { \
;     if constexpr (AF32) { _Pragma("unroll") for (int i = 0; i < 4; ++i) ld16_sc1(ra[i], Af + (size_t)i * 32 * lda + (kt_) * 32); } \
;     else { _Pragma("unroll") for (int i = 0; i < 2; ++i) ld16_sc1(rab[i], Ab + (size_t)i * 64 * lda + (kt_) * 32); } \
;     _Pragma("unroll") for (int i = 0; i < 4; ++i) ld16_sc1(rb[i], Bp + (size_t)(kt_) * bstep + i * 2048); } while (0)
; template <bool AF32, class Epi>
; __device__ __forceinline__ void gemm_tile(unsigned char* smem, const void* Ap, int lda, const bf16_t* WT, int N, int K, const Epi& epi, int m0, int n0,
;                                           GPre& pr, bool preloaded, const void* nAp, int nn0, bool has_next) {
;     ...
;   const bf16_t* Ab = (const bf16_t*)Ap + (size_t)(tid >> 2) * lda + (tid & 3) * 8;
;   const bf16_t* Bp = WT + (size_t)n0 * 32 + tid * 8;
;   const size_t bstep = (size_t)N * 32;
;   const int awf = (tid >> 3) * GLD + (tid & 7) * 4;
;   const int awb = (tid >> 2) * GLD + (tid & 3) * 8;
;     ...
;   if (!preloaded) G_LOAD(0);
;   G_STORE(0);
;   if (nk > 1) G_LOAD(1);
;   __syncthreads();
;   for (int kt = 0; kt < nk; ++kt) {
;     const int cur = kt & 1;
;     if (kt + 1 < nk) G_STORE(cur ^ 1);
;     if (kt + 2 < nk) G_LOAD(kt + 2);
;     const bf16_t* a_s = sbase + cur * G_STAGE + (wr * 64 + l15) * GLD + quad * 8;
;     const bf16_t* b_s = sbase + cur * G_STAGE + 128 * GLD + (wc * 128 + l15) * GLD + quad * 8;
; __device__ __forceinline__ void run_phase(int ph, KParams kp, unsigned char* smem) {
;     ...
;       for (int t = blockIdx.x; t < 512 * 4; t += gridDim.x) {
;         int mt, nt; tile_map(t, 4, gridDim.x, mt, nt);
;         const bool hn = t + (int)gridDim.x < 512 * 4; int mtn = 0, ntn = 0; if (hn) tile_map(t + gridDim.x, 4, gridDim.x, mtn, ntn);
;         EpiResid e{ph == 4 ? xin_row(kp->x_prompt, kp->x_sample, mt * 128) : kp->out + (size_t)mt * 128 * 1024, kp->out};
;         gemm_tile<false>(smem, A + (size_t)mt * 128 * lda, lda, Bt, 1024, K, e, mt * 128, nt * 256, pr, pre, A + (size_t)mtn * 128 * lda, ntn * 256, hn); pre = hn;
.LBB0_264:
	s_nop 0
	s_waitcnt vmcnt(0)
	v_mul_lo_u32 v32, v29, 40
	v_add_lshl_u32 v155, v32, v30, 1
	v_lshrrev_b32_e32 v250, 2, v210
	v_add_u32_e32 v251, 4, v250
	v_and_b32_e32 v251, 8, v251
	v_and_b32_e32 v252, 3, v210
	v_lshlrev_b32_e32 v252, 3, v252
	v_xor_b32_e32 v252, v252, v251
	v_mad_u32_u24 v155, v250, 40, v252
	v_lshlrev_b32_e32 v155, 1, v155
	s_ashr_i32 s3, s73, 1
	v_and_b32_e32 v31, 15, v28
	ds_write_b128 v155, v[0:3]
	ds_write_b128 v155, v[4:7] offset:5120
	ds_write_b128 v155, v[8:11] offset:10240
	ds_write_b128 v155, v[12:15] offset:15360
	ds_write_b128 v155, v[16:19] offset:20480
	ds_write_b128 v155, v[20:23] offset:25600
	v_lshl_add_u64 v[0:1], v[24:25], 0, 64
	s_andn2_b32 s3, s3, 63
	global_load_dwordx4 v[0:3], v[0:1], off sc1
	v_lshl_add_u64 v[4:5], v[24:25], 0, s[24:25]
	v_or_b32_e32 v154, s3, v31
	s_lshl_b32 s3, s73, 1
	global_load_dwordx4 v[4:7], v[4:5], off sc1
	v_lshl_add_u64 v[8:9], v[26:27], 0, s[26:27]
	s_and_b32 s53, s3, 0x80
	global_load_dwordx4 v[8:11], v[8:9], off sc1
	v_lshl_add_u64 v[12:13], v[26:27], 0, s[28:29]
	v_or_b32_e32 v24, s53, v31
	global_load_dwordx4 v[12:15], v[12:13], off sc1
	v_lshl_add_u64 v[16:17], v[26:27], 0, s[30:31]
	v_lshl_add_u64 v[20:21], v[26:27], 0, s[34:35]
	v_mul_u32_u24_e32 v165, 0x50, v24
	v_mov_b64_e32 v[24:25], s[54:55]
	v_and_b32_e32 v26, 3, v28
	global_load_dwordx4 v[16:19], v[16:17], off sc1
	v_mad_i64_i32 v[24:25], s[54:55], v29, s68, v[24:25]
	v_lshlrev_b32_e32 v26, 4, v26
	v_mov_b32_e32 v27, v153
	v_bfe_u32 v164, v28, 4, 2
	global_load_dwordx4 v[20:23], v[20:21], off sc1
	s_add_u32 s56, s65, s56
	v_lshl_add_u64 v[24:25], v[24:25], 0, v[26:27]
	v_lshlrev_b32_e32 v30, 3, v164
	s_addc_u32 s57, s66, s57
	v_lshl_add_u64 v[162:163], s[14:15], 0, v[24:25]
	v_mov_b32_e32 v24, 0
	v_mul_lo_u32 v166, v154, s67
	v_lshl_add_u64 v[160:161], v[156:157], 1, s[56:57]
	s_mov_b32 s54, 0
	v_lshlrev_b32_e32 v167, 1, v30
	v_add_u32_e32 v250, 4, v210
	v_and_b32_e32 v250, 8, v250
	v_lshlrev_b32_e32 v250, 1, v250
	v_xor_b32_e32 v167, v167, v250
	v_mov_b32_e32 v25, v24
	v_mov_b32_e32 v26, v24
	v_mov_b32_e32 v27, v24
	v_mov_b32_e32 v28, v24
	v_mov_b32_e32 v29, v24
	v_mov_b32_e32 v30, v24
	v_mov_b32_e32 v31, v24
	v_mov_b32_e32 v32, v24
	v_mov_b32_e32 v33, v24
	v_mov_b32_e32 v34, v24
	v_mov_b32_e32 v35, v24
	v_mov_b32_e32 v36, v24
	v_mov_b32_e32 v37, v24
	v_mov_b32_e32 v38, v24
	v_mov_b32_e32 v39, v24
	v_mov_b32_e32 v44, v24
	v_mov_b32_e32 v45, v24
	v_mov_b32_e32 v46, v24
	v_mov_b32_e32 v47, v24
	v_mov_b32_e32 v52, v24
	v_mov_b32_e32 v53, v24
	v_mov_b32_e32 v54, v24
	v_mov_b32_e32 v55, v24
	v_mov_b32_e32 v60, v24
	v_mov_b32_e32 v61, v24
	v_mov_b32_e32 v62, v24
	v_mov_b32_e32 v63, v24
	v_mov_b32_e32 v68, v24
	v_mov_b32_e32 v69, v24
	v_mov_b32_e32 v70, v24
	v_mov_b32_e32 v71, v24
	v_mov_b32_e32 v40, v24
	v_mov_b32_e32 v41, v24
	v_mov_b32_e32 v42, v24
	v_mov_b32_e32 v43, v24
	v_mov_b32_e32 v48, v24
	v_mov_b32_e32 v49, v24
	v_mov_b32_e32 v50, v24
	v_mov_b32_e32 v51, v24
	v_mov_b32_e32 v56, v24
	v_mov_b32_e32 v57, v24
	v_mov_b32_e32 v58, v24
	v_mov_b32_e32 v59, v24
	v_mov_b32_e32 v64, v24
	v_mov_b32_e32 v65, v24
	v_mov_b32_e32 v66, v24
	v_mov_b32_e32 v67, v24
	v_mov_b32_e32 v76, v24
	v_mov_b32_e32 v77, v24
	v_mov_b32_e32 v78, v24
	v_mov_b32_e32 v79, v24
	v_mov_b32_e32 v84, v24
	v_mov_b32_e32 v85, v24
	v_mov_b32_e32 v86, v24
	v_mov_b32_e32 v87, v24
	v_mov_b32_e32 v92, v24
	v_mov_b32_e32 v93, v24
	v_mov_b32_e32 v94, v24
	v_mov_b32_e32 v95, v24
	v_mov_b32_e32 v100, v24
	v_mov_b32_e32 v101, v24
	v_mov_b32_e32 v102, v24
	v_mov_b32_e32 v103, v24
	v_mov_b32_e32 v72, v24
	v_mov_b32_e32 v73, v24
	v_mov_b32_e32 v74, v24
	v_mov_b32_e32 v75, v24
	v_mov_b32_e32 v80, v24
	v_mov_b32_e32 v81, v24
	v_mov_b32_e32 v82, v24
	v_mov_b32_e32 v83, v24
	v_mov_b32_e32 v88, v24
	v_mov_b32_e32 v89, v24
	v_mov_b32_e32 v90, v24
	v_mov_b32_e32 v91, v24
	v_mov_b32_e32 v96, v24
	v_mov_b32_e32 v97, v24
	v_mov_b32_e32 v98, v24
	v_mov_b32_e32 v99, v24
	v_mov_b32_e32 v108, v24
	v_mov_b32_e32 v109, v24
	v_mov_b32_e32 v110, v24
	v_mov_b32_e32 v111, v24
	v_mov_b32_e32 v116, v24
	v_mov_b32_e32 v117, v24
	v_mov_b32_e32 v118, v24
	v_mov_b32_e32 v119, v24
	v_mov_b32_e32 v128, v24
	v_mov_b32_e32 v129, v24
	v_mov_b32_e32 v130, v24
	v_mov_b32_e32 v131, v24
	v_mov_b32_e32 v132, v24
	v_mov_b32_e32 v133, v24
	v_mov_b32_e32 v134, v24
	v_mov_b32_e32 v135, v24
	v_mov_b32_e32 v104, v24
	v_mov_b32_e32 v105, v24
	v_mov_b32_e32 v106, v24
	v_mov_b32_e32 v107, v24
	v_mov_b32_e32 v112, v24
	v_mov_b32_e32 v113, v24
	v_mov_b32_e32 v114, v24
	v_mov_b32_e32 v115, v24
	v_mov_b32_e32 v120, v24
	v_mov_b32_e32 v121, v24
	v_mov_b32_e32 v122, v24
	v_mov_b32_e32 v123, v24
	v_mov_b32_e32 v124, v24
	v_mov_b32_e32 v125, v24
	v_mov_b32_e32 v126, v24
	v_mov_b32_e32 v127, v24
	v_mov_b32_e32 v136, v24
	v_mov_b32_e32 v137, v24
	v_mov_b32_e32 v138, v24
	v_mov_b32_e32 v139, v24
	v_mov_b32_e32 v140, v24
	v_mov_b32_e32 v141, v24
	v_mov_b32_e32 v142, v24
	v_mov_b32_e32 v143, v24
	v_mov_b32_e32 v144, v24
	v_mov_b32_e32 v145, v24
	v_mov_b32_e32 v146, v24
	v_mov_b32_e32 v147, v24
	v_mov_b32_e32 v148, v24
	v_mov_b32_e32 v149, v24
	v_mov_b32_e32 v150, v24
	v_mov_b32_e32 v151, v24
	s_waitcnt lgkmcnt(0)
	s_barrier

; #define G_LOAD(kt_) do { \
;     if constexpr (AF32) { _Pragma("unroll") for (int i = 0; i < 4; ++i) ld16_sc1(ra[i], Af + (size_t)i * 32 * lda + (kt_) * 32); } \
;     else { _Pragma("unroll") for (int i = 0; i < 2; ++i) ld16_sc1(rab[i], Ab + (size_t)i * 64 * lda + (kt_) * 32); } \
;     _Pragma("unroll") for (int i = 0; i < 4; ++i) ld16_sc1(rb[i], Bp + (size_t)(kt_) * bstep + i * 2048); } while (0)
; template <bool AF32, class Epi>
; __device__ __forceinline__ void gemm_tile(unsigned char* smem, const void* Ap, int lda, const bf16_t* WT, int N, int K, const Epi& epi, int m0, int n0,
;                                           GPre& pr, bool preloaded, const void* nAp, int nn0, bool has_next) {
;     ...
;   const float* Af = (const float*)Ap + (size_t)(tid >> 3) * lda + (tid & 7) * 4;
;   const bf16_t* Ab = (const bf16_t*)Ap + (size_t)(tid >> 2) * lda + (tid & 3) * 8;
;   const bf16_t* Bp = WT + (size_t)n0 * 32 + tid * 8;
;   const size_t bstep = (size_t)N * 32;
;   const int awf = (tid >> 3) * GLD + (tid & 7) * 4;
;   const int awb = (tid >> 2) * GLD + (tid & 3) * 8;
;     ...
;   if (!preloaded) G_LOAD(0);
;   G_STORE(0);
;   if (nk > 1) G_LOAD(1);
;   __syncthreads();
;   for (int kt = 0; kt < nk; ++kt) {
;     const int cur = kt & 1;
;     if (kt + 1 < nk) G_STORE(cur ^ 1);
;     if (kt + 2 < nk) G_LOAD(kt + 2);
;     const bf16_t* a_s = sbase + cur * G_STAGE + (wr * 64 + l15) * GLD + quad * 8;
;     const bf16_t* b_s = sbase + cur * G_STAGE + 128 * GLD + (wc * 128 + l15) * GLD + quad * 8;
.LBB0_295:
	v_and_b32_e32 v52, 15, v18
	v_bfe_u32 v53, v18, 4, 2
	v_lshrrev_b32_e32 v19, 2, v18
	v_and_b32_e32 v18, 24, v184
	s_waitcnt vmcnt(0)
	v_mad_u64_u32 v[162:163], s[66:67], v19, 40, v[18:19]
	v_lshrrev_b32_e32 v250, 2, v210
	v_add_u32_e32 v251, 4, v250
	v_and_b32_e32 v251, 8, v251
	v_and_b32_e32 v252, 3, v210
	v_lshlrev_b32_e32 v252, 3, v252
	v_xor_b32_e32 v252, v252, v251
	v_mad_u32_u24 v162, v250, 40, v252
	v_cvt_pk_bf16_f32 v18, v40, v41
	v_mov_b32_e32 v21, v40
	v_mov_b32_e32 v40, v45
	v_mov_b32_e32 v20, v44
	v_pk_mul_f32 v[22:23], v[40:41], v[40:41]
	v_lshlrev_b32_e32 v190, 2, v179
	v_pk_fma_f32 v[20:21], v[20:21], v[20:21], v[22:23]
	v_mov_b32_e32 v22, v46
	v_mov_b32_e32 v23, v42
	v_mad_u64_u32 v[160:161], s[66:67], v180, 40, v[190:191]
	v_lshrrev_b32_e32 v250, 3, v210
	v_add_u32_e32 v251, 4, v250
	v_and_b32_e32 v251, 8, v251
	v_and_b32_e32 v252, 7, v210
	v_lshlrev_b32_e32 v252, 2, v252
	v_xor_b32_e32 v252, v252, v251
	v_mad_u32_u24 v160, v250, 40, v252
	v_cvt_pk_bf16_f32 v19, v42, v43
	v_pk_fma_f32 v[20:21], v[22:23], v[22:23], v[20:21]
	v_mov_b32_e32 v42, v47
	v_lshlrev_b32_e32 v161, 1, v160
	v_pk_fma_f32 v[186:187], v[42:43], v[42:43], v[20:21]
	v_cvt_pk_bf16_f32 v20, v44, v45
	v_cvt_pk_bf16_f32 v21, v46, v47
	ds_write2st64_b64 v161, v[18:19], v[20:21] offset1:5
	v_cvt_pk_bf16_f32 v18, v32, v33
	v_mov_b32_e32 v21, v32
	v_mov_b32_e32 v32, v37
	v_mov_b32_e32 v20, v36
	v_pk_mul_f32 v[22:23], v[32:33], v[32:33]
	v_cvt_pk_bf16_f32 v19, v34, v35
	v_pk_fma_f32 v[20:21], v[20:21], v[20:21], v[22:23]
	v_mov_b32_e32 v22, v38
	v_mov_b32_e32 v23, v34
	v_pk_fma_f32 v[20:21], v[22:23], v[22:23], v[20:21]
	v_mov_b32_e32 v34, v39
	v_pk_fma_f32 v[182:183], v[34:35], v[34:35], v[20:21]
	v_cvt_pk_bf16_f32 v20, v36, v37
	v_cvt_pk_bf16_f32 v21, v38, v39
	v_lshlrev_b32_e32 v163, 1, v162
	ds_write2st64_b64 v161, v[18:19], v[20:21] offset0:10 offset1:15
	ds_write_b128 v163, v[0:3] offset:10240
	ds_write_b128 v163, v[4:7] offset:15360
	ds_write_b128 v163, v[8:11] offset:20480
	ds_write_b128 v163, v[12:15] offset:25600
	v_lshl_add_u64 v[0:1], v[16:17], 0, s[26:27]
	global_load_dwordx4 v[28:31], v[0:1], off sc1
	v_lshl_add_u64 v[0:1], v[16:17], 0, s[28:29]
	global_load_dwordx4 v[24:27], v[0:1], off sc1
	v_lshl_add_u64 v[0:1], v[16:17], 0, s[30:31]
	s_ashr_i32 s3, s47, 1
	global_load_dwordx4 v[20:23], v[0:1], off sc1
	v_lshl_add_u64 v[0:1], v[16:17], 0, s[34:35]
	s_andn2_b32 s3, s3, 63
	v_lshlrev_b64 v[188:189], 10, v[180:181]
	global_load_dwordx4 v[16:19], v[0:1], off sc1
	v_lshl_add_u64 v[0:1], v[50:51], 0, s[36:37]
	v_or_b32_e32 v181, s3, v52
	s_lshl_b32 s3, s47, 1
	global_load_dwordx4 v[0:3], v[0:1], off sc1
	v_lshl_add_u64 v[4:5], v[50:51], 0, s[38:39]
	s_and_b32 s47, s3, 0x80
	global_load_dwordx4 v[4:7], v[4:5], off sc1
	v_lshl_add_u64 v[8:9], v[50:51], 0, s[40:41]
	v_or_b32_e32 v32, s47, v52
	global_load_dwordx4 v[8:11], v[8:9], off sc1
	v_lshl_add_u64 v[12:13], v[50:51], 0, s[42:43]
	v_mul_u32_u24_e32 v168, 0x50, v32
	v_lshl_add_u64 v[32:33], s[52:53], 0, v[48:49]
	global_load_dwordx4 v[12:15], v[12:13], off sc1
	s_add_u32 s54, s60, s54
	v_lshl_add_u64 v[32:33], v[32:33], 0, v[176:177]
	v_lshlrev_b32_e32 v178, 3, v53
	s_addc_u32 s55, s61, s55
	v_lshl_add_u64 v[166:167], s[12:13], 0, v[32:33]
	v_mov_b32_e32 v32, 0
	v_mul_lo_u32 v169, v181, s62
	v_lshl_add_u64 v[164:165], v[184:185], 1, s[54:55]
	s_mov_b32 s49, 0
	v_lshlrev_b32_e32 v170, 1, v178
	v_add_u32_e32 v250, 4, v210
	v_and_b32_e32 v250, 8, v250
	v_lshlrev_b32_e32 v250, 1, v250
	v_xor_b32_e32 v170, v170, v250
	v_mov_b32_e32 v33, v32
	v_mov_b32_e32 v34, v32
	v_mov_b32_e32 v35, v32
	v_mov_b32_e32 v36, v32
	v_mov_b32_e32 v37, v32
	v_mov_b32_e32 v38, v32
	v_mov_b32_e32 v39, v32
	v_mov_b32_e32 v40, v32
	v_mov_b32_e32 v41, v32
	v_mov_b32_e32 v42, v32
	v_mov_b32_e32 v43, v32
	v_mov_b32_e32 v44, v32
	v_mov_b32_e32 v45, v32
	v_mov_b32_e32 v46, v32
	v_mov_b32_e32 v47, v32
	v_mov_b32_e32 v52, v32
	v_mov_b32_e32 v53, v32
	v_mov_b32_e32 v54, v32
	v_mov_b32_e32 v55, v32
	v_mov_b32_e32 v60, v32
	v_mov_b32_e32 v61, v32
	v_mov_b32_e32 v62, v32
	v_mov_b32_e32 v63, v32
	v_mov_b32_e32 v68, v32
	v_mov_b32_e32 v69, v32
	v_mov_b32_e32 v70, v32
	v_mov_b32_e32 v71, v32
	v_mov_b32_e32 v76, v32
	v_mov_b32_e32 v77, v32
	v_mov_b32_e32 v78, v32
	v_mov_b32_e32 v79, v32
	v_mov_b32_e32 v48, v32
	v_mov_b32_e32 v49, v32
	v_mov_b32_e32 v50, v32
	v_mov_b32_e32 v51, v32
	v_mov_b32_e32 v56, v32
	v_mov_b32_e32 v57, v32
	v_mov_b32_e32 v58, v32
	v_mov_b32_e32 v59, v32
	v_mov_b32_e32 v64, v32
	v_mov_b32_e32 v65, v32
	v_mov_b32_e32 v66, v32
	v_mov_b32_e32 v67, v32
	v_mov_b32_e32 v72, v32
	v_mov_b32_e32 v73, v32
	v_mov_b32_e32 v74, v32
	v_mov_b32_e32 v75, v32
	v_mov_b32_e32 v84, v32
	v_mov_b32_e32 v85, v32
	v_mov_b32_e32 v86, v32
	v_mov_b32_e32 v87, v32
	v_mov_b32_e32 v92, v32
	v_mov_b32_e32 v93, v32
	v_mov_b32_e32 v94, v32
	v_mov_b32_e32 v95, v32
	v_mov_b32_e32 v100, v32
	v_mov_b32_e32 v101, v32
	v_mov_b32_e32 v102, v32
	v_mov_b32_e32 v103, v32
	v_mov_b32_e32 v108, v32
	v_mov_b32_e32 v109, v32
	v_mov_b32_e32 v110, v32
	v_mov_b32_e32 v111, v32
	v_mov_b32_e32 v80, v32
	v_mov_b32_e32 v81, v32
	v_mov_b32_e32 v82, v32
	v_mov_b32_e32 v83, v32
	v_mov_b32_e32 v88, v32
	v_mov_b32_e32 v89, v32
	v_mov_b32_e32 v90, v32
	v_mov_b32_e32 v91, v32
	v_mov_b32_e32 v96, v32
	v_mov_b32_e32 v97, v32
	v_mov_b32_e32 v98, v32
	v_mov_b32_e32 v99, v32
	v_mov_b32_e32 v104, v32
	v_mov_b32_e32 v105, v32
	v_mov_b32_e32 v106, v32
	v_mov_b32_e32 v107, v32
	v_mov_b32_e32 v116, v32
	v_mov_b32_e32 v117, v32
	v_mov_b32_e32 v118, v32
	v_mov_b32_e32 v119, v32
	v_mov_b32_e32 v124, v32
	v_mov_b32_e32 v125, v32
	v_mov_b32_e32 v126, v32
	v_mov_b32_e32 v127, v32
	v_mov_b32_e32 v136, v32
	v_mov_b32_e32 v137, v32
	v_mov_b32_e32 v138, v32
	v_mov_b32_e32 v139, v32
	v_mov_b32_e32 v140, v32
	v_mov_b32_e32 v141, v32
	v_mov_b32_e32 v142, v32
	v_mov_b32_e32 v143, v32
	v_mov_b32_e32 v112, v32
	v_mov_b32_e32 v113, v32
	v_mov_b32_e32 v114, v32
	v_mov_b32_e32 v115, v32
	v_mov_b32_e32 v120, v32
	v_mov_b32_e32 v121, v32
	v_mov_b32_e32 v122, v32
	v_mov_b32_e32 v123, v32
	v_mov_b32_e32 v128, v32
	v_mov_b32_e32 v129, v32
	v_mov_b32_e32 v130, v32
	v_mov_b32_e32 v131, v32
	v_mov_b32_e32 v132, v32
	v_mov_b32_e32 v133, v32
	v_mov_b32_e32 v134, v32
	v_mov_b32_e32 v135, v32
	v_mov_b32_e32 v144, v32
	v_mov_b32_e32 v145, v32
	v_mov_b32_e32 v146, v32
	v_mov_b32_e32 v147, v32
	v_mov_b32_e32 v148, v32
	v_mov_b32_e32 v149, v32
	v_mov_b32_e32 v150, v32
	v_mov_b32_e32 v151, v32
	v_mov_b32_e32 v152, v32
	v_mov_b32_e32 v153, v32
	v_mov_b32_e32 v154, v32
	v_mov_b32_e32 v155, v32
	v_mov_b32_e32 v156, v32
	v_mov_b32_e32 v157, v32
	v_mov_b32_e32 v158, v32
	v_mov_b32_e32 v159, v32
	s_waitcnt lgkmcnt(0)
	s_barrier

; #define G_LOAD(kt_) do { \
;     if constexpr (AF32) { _Pragma("unroll") for (int i = 0; i < 4; ++i) ld16_sc1(ra[i], Af + (size_t)i * 32 * lda + (kt_) * 32); } \
;     else { _Pragma("unroll") for (int i = 0; i < 2; ++i) ld16_sc1(rab[i], Ab + (size_t)i * 64 * lda + (kt_) * 32); } \
;     _Pragma("unroll") for (int i = 0; i < 4; ++i) ld16_sc1(rb[i], Bp + (size_t)(kt_) * bstep + i * 2048); } while (0)
; template <bool AF32, class Epi>
; __device__ __forceinline__ void gemm_tile(unsigned char* smem, const void* Ap, int lda, const bf16_t* WT, int N, int K, const Epi& epi, int m0, int n0,
;                                           GPre& pr, bool preloaded, const void* nAp, int nn0, bool has_next) {
;     ...
;   const bf16_t* Ab = (const bf16_t*)Ap + (size_t)(tid >> 2) * lda + (tid & 3) * 8;
;   const bf16_t* Bp = WT + (size_t)n0 * 32 + tid * 8;
;   const size_t bstep = (size_t)N * 32;
;   const int awf = (tid >> 3) * GLD + (tid & 7) * 4;
;   const int awb = (tid >> 2) * GLD + (tid & 3) * 8;
;     ...
;   if (!preloaded) G_LOAD(0);
;   G_STORE(0);
;   if (nk > 1) G_LOAD(1);
;   __syncthreads();
;   for (int kt = 0; kt < nk; ++kt) {
;     const int cur = kt & 1;
;     if (kt + 1 < nk) G_STORE(cur ^ 1);
;     if (kt + 2 < nk) G_LOAD(kt + 2);
;     const bf16_t* a_s = sbase + cur * G_STAGE + (wr * 64 + l15) * GLD + quad * 8;
;     const bf16_t* b_s = sbase + cur * G_STAGE + 128 * GLD + (wc * 128 + l15) * GLD + quad * 8;
.LBB0_357:
	s_nop 0
	s_waitcnt vmcnt(0)
	v_lshlrev_b64 v[158:159], 10, v[30:31]
	v_mul_lo_u32 v30, v30, 40
	v_add_lshl_u32 v155, v30, v33, 1
	v_lshrrev_b32_e32 v250, 2, v210
	v_add_u32_e32 v251, 4, v250
	v_and_b32_e32 v251, 8, v251
	v_and_b32_e32 v252, 3, v210
	v_lshlrev_b32_e32 v252, 3, v252
	v_xor_b32_e32 v252, v252, v251
	v_mad_u32_u24 v155, v250, 40, v252
	v_lshlrev_b32_e32 v155, 1, v155
	s_ashr_i32 s3, s53, 1
	v_and_b32_e32 v31, 15, v32
	ds_write_b128 v155, v[0:3]
	ds_write_b128 v155, v[4:7] offset:5120
	ds_write_b128 v155, v[8:11] offset:10240
	ds_write_b128 v155, v[12:15] offset:15360
	ds_write_b128 v155, v[16:19] offset:20480
	ds_write_b128 v155, v[20:23] offset:25600
	v_lshl_add_u64 v[0:1], v[26:27], 0, 64
	s_andn2_b32 s3, s3, 63
	global_load_dwordx4 v[0:3], v[0:1], off sc1
	v_lshl_add_u64 v[4:5], v[26:27], 0, s[20:21]
	v_or_b32_e32 v154, s3, v31
	s_lshl_b32 s3, s53, 1
	global_load_dwordx4 v[4:7], v[4:5], off sc1
	v_lshl_add_u64 v[8:9], v[28:29], 0, s[22:23]
	s_and_b32 s51, s3, 0x80
	global_load_dwordx4 v[8:11], v[8:9], off sc1
	v_lshl_add_u64 v[12:13], v[28:29], 0, s[24:25]
	v_or_b32_e32 v26, s51, v31
	global_load_dwordx4 v[12:15], v[12:13], off sc1
	v_lshl_add_u64 v[16:17], v[28:29], 0, s[26:27]
	v_mul_u32_u24_e32 v165, 0x50, v26
	v_and_b32_e32 v26, 3, v32
	global_load_dwordx4 v[16:19], v[16:17], off sc1
	v_lshl_add_u64 v[20:21], v[28:29], 0, s[28:29]
	v_lshl_add_u64 v[24:25], s[54:55], 0, v[24:25]
	v_lshlrev_b32_e32 v26, 4, v26
	v_mov_b32_e32 v27, v153
	v_bfe_u32 v164, v32, 4, 2
	global_load_dwordx4 v[20:23], v[20:21], off sc1
	s_add_u32 s56, s64, s56
	v_lshl_add_u64 v[24:25], v[24:25], 0, v[26:27]
	v_lshlrev_b32_e32 v28, 3, v164
	s_addc_u32 s57, s65, s57
	v_lshl_add_u64 v[162:163], s[10:11], 0, v[24:25]
	v_mov_b32_e32 v24, 0
	v_mul_lo_u32 v166, v154, s66
	v_lshl_add_u64 v[160:161], v[156:157], 1, s[56:57]
	s_mov_b32 s53, 0
	v_lshlrev_b32_e32 v167, 1, v28
	v_add_u32_e32 v250, 4, v210
	v_and_b32_e32 v250, 8, v250
	v_lshlrev_b32_e32 v250, 1, v250
	v_xor_b32_e32 v167, v167, v250
	v_mov_b32_e32 v25, v24
	v_mov_b32_e32 v26, v24
	v_mov_b32_e32 v27, v24
	v_mov_b32_e32 v28, v24
	v_mov_b32_e32 v29, v24
	v_mov_b32_e32 v30, v24
	v_mov_b32_e32 v31, v24
	v_mov_b32_e32 v32, v24
	v_mov_b32_e32 v33, v24
	v_mov_b32_e32 v34, v24
	v_mov_b32_e32 v35, v24
	v_mov_b32_e32 v36, v24
	v_mov_b32_e32 v37, v24
	v_mov_b32_e32 v38, v24
	v_mov_b32_e32 v39, v24
	v_mov_b32_e32 v44, v24
	v_mov_b32_e32 v45, v24
	v_mov_b32_e32 v46, v24
	v_mov_b32_e32 v47, v24
	v_mov_b32_e32 v52, v24
	v_mov_b32_e32 v53, v24
	v_mov_b32_e32 v54, v24
	v_mov_b32_e32 v55, v24
	v_mov_b32_e32 v60, v24
	v_mov_b32_e32 v61, v24
	v_mov_b32_e32 v62, v24
	v_mov_b32_e32 v63, v24
	v_mov_b32_e32 v68, v24
	v_mov_b32_e32 v69, v24
	v_mov_b32_e32 v70, v24
	v_mov_b32_e32 v71, v24
	v_mov_b32_e32 v40, v24
	v_mov_b32_e32 v41, v24
	v_mov_b32_e32 v42, v24
	v_mov_b32_e32 v43, v24
	v_mov_b32_e32 v48, v24
	v_mov_b32_e32 v49, v24
	v_mov_b32_e32 v50, v24
	v_mov_b32_e32 v51, v24
	v_mov_b32_e32 v56, v24
	v_mov_b32_e32 v57, v24
	v_mov_b32_e32 v58, v24
	v_mov_b32_e32 v59, v24
	v_mov_b32_e32 v64, v24
	v_mov_b32_e32 v65, v24
	v_mov_b32_e32 v66, v24
	v_mov_b32_e32 v67, v24
	v_mov_b32_e32 v76, v24
	v_mov_b32_e32 v77, v24
	v_mov_b32_e32 v78, v24
	v_mov_b32_e32 v79, v24
	v_mov_b32_e32 v84, v24
	v_mov_b32_e32 v85, v24
	v_mov_b32_e32 v86, v24
	v_mov_b32_e32 v87, v24
	v_mov_b32_e32 v92, v24
	v_mov_b32_e32 v93, v24
	v_mov_b32_e32 v94, v24
	v_mov_b32_e32 v95, v24
	v_mov_b32_e32 v100, v24
	v_mov_b32_e32 v101, v24
	v_mov_b32_e32 v102, v24
	v_mov_b32_e32 v103, v24
	v_mov_b32_e32 v72, v24
	v_mov_b32_e32 v73, v24
	v_mov_b32_e32 v74, v24
	v_mov_b32_e32 v75, v24
	v_mov_b32_e32 v80, v24
	v_mov_b32_e32 v81, v24
	v_mov_b32_e32 v82, v24
	v_mov_b32_e32 v83, v24
	v_mov_b32_e32 v88, v24
	v_mov_b32_e32 v89, v24
	v_mov_b32_e32 v90, v24
	v_mov_b32_e32 v91, v24
	v_mov_b32_e32 v96, v24
	v_mov_b32_e32 v97, v24
	v_mov_b32_e32 v98, v24
	v_mov_b32_e32 v99, v24
	v_mov_b32_e32 v108, v24
	v_mov_b32_e32 v109, v24
	v_mov_b32_e32 v110, v24
	v_mov_b32_e32 v111, v24
	v_mov_b32_e32 v116, v24
	v_mov_b32_e32 v117, v24
	v_mov_b32_e32 v118, v24
	v_mov_b32_e32 v119, v24
	v_mov_b32_e32 v128, v24
	v_mov_b32_e32 v129, v24
	v_mov_b32_e32 v130, v24
	v_mov_b32_e32 v131, v24
	v_mov_b32_e32 v132, v24
	v_mov_b32_e32 v133, v24
	v_mov_b32_e32 v134, v24
	v_mov_b32_e32 v135, v24
	v_mov_b32_e32 v104, v24
	v_mov_b32_e32 v105, v24
	v_mov_b32_e32 v106, v24
	v_mov_b32_e32 v107, v24
	v_mov_b32_e32 v112, v24
	v_mov_b32_e32 v113, v24
	v_mov_b32_e32 v114, v24
	v_mov_b32_e32 v115, v24
	v_mov_b32_e32 v120, v24
	v_mov_b32_e32 v121, v24
	v_mov_b32_e32 v122, v24
	v_mov_b32_e32 v123, v24
	v_mov_b32_e32 v124, v24
	v_mov_b32_e32 v125, v24
	v_mov_b32_e32 v126, v24
	v_mov_b32_e32 v127, v24
	v_mov_b32_e32 v136, v24
	v_mov_b32_e32 v137, v24
	v_mov_b32_e32 v138, v24
	v_mov_b32_e32 v139, v24
	v_mov_b32_e32 v140, v24
	v_mov_b32_e32 v141, v24
	v_mov_b32_e32 v142, v24
	v_mov_b32_e32 v143, v24
	v_mov_b32_e32 v144, v24
	v_mov_b32_e32 v145, v24
	v_mov_b32_e32 v146, v24
	v_mov_b32_e32 v147, v24
	v_mov_b32_e32 v148, v24
	v_mov_b32_e32 v149, v24
	v_mov_b32_e32 v150, v24
	v_mov_b32_e32 v151, v24
	s_waitcnt lgkmcnt(0)
	s_barrier

; #define G_LOAD(kt_) do { \
;     if constexpr (AF32) { _Pragma("unroll") for (int i = 0; i < 4; ++i) ld16_sc1(ra[i], Af + (size_t)i * 32 * lda + (kt_) * 32); } \
;     else { _Pragma("unroll") for (int i = 0; i < 2; ++i) ld16_sc1(rab[i], Ab + (size_t)i * 64 * lda + (kt_) * 32); } \
;     _Pragma("unroll") for (int i = 0; i < 4; ++i) ld16_sc1(rb[i], Bp + (size_t)(kt_) * bstep + i * 2048); } while (0)
; template <bool AF32, class Epi>
; __device__ __forceinline__ void gemm_tile(unsigned char* smem, const void* Ap, int lda, const bf16_t* WT, int N, int K, const Epi& epi, int m0, int n0,
;                                           GPre& pr, bool preloaded, const void* nAp, int nn0, bool has_next) {
;     ...
;   const float* Af = (const float*)Ap + (size_t)(tid >> 3) * lda + (tid & 7) * 4;
;   const bf16_t* Ab = (const bf16_t*)Ap + (size_t)(tid >> 2) * lda + (tid & 3) * 8;
;   const bf16_t* Bp = WT + (size_t)n0 * 32 + tid * 8;
;   const size_t bstep = (size_t)N * 32;
;   const int awf = (tid >> 3) * GLD + (tid & 7) * 4;
;   const int awb = (tid >> 2) * GLD + (tid & 3) * 8;
;     ...
;   if (!preloaded) G_LOAD(0);
;   G_STORE(0);
;   if (nk > 1) G_LOAD(1);
;   __syncthreads();
;   for (int kt = 0; kt < nk; ++kt) {
;     const int cur = kt & 1;
;     if (kt + 1 < nk) G_STORE(cur ^ 1);
;     if (kt + 2 < nk) G_LOAD(kt + 2);
;     const bf16_t* a_s = sbase + cur * G_STAGE + (wr * 64 + l15) * GLD + quad * 8;
;     const bf16_t* b_s = sbase + cur * G_STAGE + 128 * GLD + (wc * 128 + l15) * GLD + quad * 8;
.LBB0_388:
	v_lshlrev_b64 v[186:187], 10, v[178:179]
	v_and_b32_e32 v52, 15, v34
	v_bfe_u32 v179, v34, 4, 2
	v_lshrrev_b32_e32 v35, 2, v34
	v_and_b32_e32 v34, 24, v182
	s_waitcnt vmcnt(0)
	v_mad_u64_u32 v[162:163], s[68:69], v35, 40, v[34:35]
	v_lshrrev_b32_e32 v250, 2, v210
	v_add_u32_e32 v251, 4, v250
	v_and_b32_e32 v251, 8, v251
	v_and_b32_e32 v252, 3, v210
	v_lshlrev_b32_e32 v252, 3, v252
	v_xor_b32_e32 v252, v252, v251
	v_mad_u32_u24 v162, v250, 40, v252
	v_cvt_pk_bf16_f32 v34, v24, v25
	v_mov_b32_e32 v37, v24
	v_mov_b32_e32 v24, v29
	v_mov_b32_e32 v36, v28
	v_pk_mul_f32 v[24:25], v[24:25], v[24:25]
	v_lshlrev_b32_e32 v188, 2, v191
	v_pk_fma_f32 v[24:25], v[36:37], v[36:37], v[24:25]
	v_mov_b32_e32 v36, v30
	v_mov_b32_e32 v37, v26
	v_mad_u64_u32 v[160:161], s[68:69], v178, 40, v[188:189]
	v_lshrrev_b32_e32 v250, 3, v210
	v_add_u32_e32 v251, 4, v250
	v_and_b32_e32 v251, 8, v251
	v_and_b32_e32 v252, 7, v210
	v_lshlrev_b32_e32 v252, 2, v252
	v_xor_b32_e32 v252, v252, v251
	v_mad_u32_u24 v160, v250, 40, v252
	v_cvt_pk_bf16_f32 v35, v26, v27
	v_pk_fma_f32 v[24:25], v[36:37], v[36:37], v[24:25]
	v_mov_b32_e32 v26, v31
	v_lshlrev_b32_e32 v161, 1, v160
	v_pk_fma_f32 v[184:185], v[26:27], v[26:27], v[24:25]
	v_cvt_pk_bf16_f32 v24, v28, v29
	v_cvt_pk_bf16_f32 v25, v30, v31
	ds_write2st64_b64 v161, v[34:35], v[24:25] offset1:5
	v_cvt_pk_bf16_f32 v24, v16, v17
	v_mov_b32_e32 v27, v16
	v_mov_b32_e32 v16, v21
	v_mov_b32_e32 v26, v20
	v_pk_mul_f32 v[16:17], v[16:17], v[16:17]
	v_cvt_pk_bf16_f32 v25, v18, v19
	v_pk_fma_f32 v[16:17], v[26:27], v[26:27], v[16:17]
	v_mov_b32_e32 v26, v22
	v_mov_b32_e32 v27, v18
	v_pk_fma_f32 v[16:17], v[26:27], v[26:27], v[16:17]
	v_mov_b32_e32 v18, v23
	v_pk_fma_f32 v[180:181], v[18:19], v[18:19], v[16:17]
	v_cvt_pk_bf16_f32 v16, v20, v21
	v_cvt_pk_bf16_f32 v17, v22, v23
	v_lshlrev_b32_e32 v163, 1, v162
	ds_write2st64_b64 v161, v[24:25], v[16:17] offset0:10 offset1:15
	ds_write_b128 v163, v[0:3] offset:10240
	ds_write_b128 v163, v[4:7] offset:15360
	ds_write_b128 v163, v[8:11] offset:20480
	ds_write_b128 v163, v[12:15] offset:25600
	v_lshl_add_u64 v[0:1], v[32:33], 0, s[28:29]
	global_load_dwordx4 v[44:47], v[0:1], off sc1
	v_lshl_add_u64 v[0:1], v[32:33], 0, s[30:31]
	global_load_dwordx4 v[40:43], v[0:1], off sc1
	v_lshl_add_u64 v[0:1], v[32:33], 0, s[34:35]
	s_ashr_i32 s3, s49, 1
	global_load_dwordx4 v[36:39], v[0:1], off sc1
	v_lshl_add_u64 v[0:1], v[32:33], 0, s[36:37]
	s_andn2_b32 s3, s3, 63
	global_load_dwordx4 v[32:35], v[0:1], off sc1
	v_lshl_add_u64 v[0:1], v[50:51], 0, s[38:39]
	v_or_b32_e32 v192, s3, v52
	s_lshl_b32 s3, s49, 1
	global_load_dwordx4 v[0:3], v[0:1], off sc1
	v_lshl_add_u64 v[4:5], v[50:51], 0, s[40:41]
	s_and_b32 s3, s3, 0x80
	global_load_dwordx4 v[4:7], v[4:5], off sc1
	v_lshl_add_u64 v[8:9], v[50:51], 0, s[42:43]
	v_or_b32_e32 v16, s3, v52
	global_load_dwordx4 v[8:11], v[8:9], off sc1
	v_lshl_add_u64 v[12:13], v[50:51], 0, s[44:45]
	v_mul_u32_u24_e32 v168, 0x50, v16
	v_lshl_add_u64 v[16:17], s[52:53], 0, v[48:49]
	global_load_dwordx4 v[12:15], v[12:13], off sc1
	s_add_u32 s54, s60, s54
	v_lshl_add_u64 v[16:17], v[16:17], 0, v[176:177]
	v_lshlrev_b32_e32 v18, 3, v179
	s_addc_u32 s55, s61, s55
	v_lshl_add_u64 v[166:167], s[14:15], 0, v[16:17]
	v_mov_b32_e32 v16, 0
	v_mul_lo_u32 v169, v192, s62
	v_lshl_add_u64 v[164:165], v[182:183], 1, s[54:55]
	s_mov_b32 s51, 0
	v_lshlrev_b32_e32 v170, 1, v18
	v_add_u32_e32 v250, 4, v210
	v_and_b32_e32 v250, 8, v250
	v_lshlrev_b32_e32 v250, 1, v250
	v_xor_b32_e32 v170, v170, v250
	v_mov_b32_e32 v17, v16
	v_mov_b32_e32 v18, v16
	v_mov_b32_e32 v19, v16
	v_mov_b32_e32 v20, v16
	v_mov_b32_e32 v21, v16
	v_mov_b32_e32 v22, v16
	v_mov_b32_e32 v23, v16
	v_mov_b32_e32 v24, v16
	v_mov_b32_e32 v25, v16
	v_mov_b32_e32 v26, v16
	v_mov_b32_e32 v27, v16
	v_mov_b32_e32 v28, v16
	v_mov_b32_e32 v29, v16
	v_mov_b32_e32 v30, v16
	v_mov_b32_e32 v31, v16
	v_mov_b32_e32 v52, v16
	v_mov_b32_e32 v53, v16
	v_mov_b32_e32 v54, v16
	v_mov_b32_e32 v55, v16
	v_mov_b32_e32 v60, v16
	v_mov_b32_e32 v61, v16
	v_mov_b32_e32 v62, v16
	v_mov_b32_e32 v63, v16
	v_mov_b32_e32 v68, v16
	v_mov_b32_e32 v69, v16
	v_mov_b32_e32 v70, v16
	v_mov_b32_e32 v71, v16
	v_mov_b32_e32 v76, v16
	v_mov_b32_e32 v77, v16
	v_mov_b32_e32 v78, v16
	v_mov_b32_e32 v79, v16
	v_mov_b32_e32 v48, v16
	v_mov_b32_e32 v49, v16
	v_mov_b32_e32 v50, v16
	v_mov_b32_e32 v51, v16
	v_mov_b32_e32 v56, v16
	v_mov_b32_e32 v57, v16
	v_mov_b32_e32 v58, v16
	v_mov_b32_e32 v59, v16
	v_mov_b32_e32 v64, v16
	v_mov_b32_e32 v65, v16
	v_mov_b32_e32 v66, v16
	v_mov_b32_e32 v67, v16
	v_mov_b32_e32 v72, v16
	v_mov_b32_e32 v73, v16
	v_mov_b32_e32 v74, v16
	v_mov_b32_e32 v75, v16
	v_mov_b32_e32 v84, v16
	v_mov_b32_e32 v85, v16
	v_mov_b32_e32 v86, v16
	v_mov_b32_e32 v87, v16
	v_mov_b32_e32 v92, v16
	v_mov_b32_e32 v93, v16
	v_mov_b32_e32 v94, v16
	v_mov_b32_e32 v95, v16
	v_mov_b32_e32 v100, v16
	v_mov_b32_e32 v101, v16
	v_mov_b32_e32 v102, v16
	v_mov_b32_e32 v103, v16
	v_mov_b32_e32 v108, v16
	v_mov_b32_e32 v109, v16
	v_mov_b32_e32 v110, v16
	v_mov_b32_e32 v111, v16
	v_mov_b32_e32 v80, v16
	v_mov_b32_e32 v81, v16
	v_mov_b32_e32 v82, v16
	v_mov_b32_e32 v83, v16
	v_mov_b32_e32 v88, v16
	v_mov_b32_e32 v89, v16
	v_mov_b32_e32 v90, v16
	v_mov_b32_e32 v91, v16
	v_mov_b32_e32 v96, v16
	v_mov_b32_e32 v97, v16
	v_mov_b32_e32 v98, v16
	v_mov_b32_e32 v99, v16
	v_mov_b32_e32 v104, v16
	v_mov_b32_e32 v105, v16
	v_mov_b32_e32 v106, v16
	v_mov_b32_e32 v107, v16
	v_mov_b32_e32 v116, v16
	v_mov_b32_e32 v117, v16
	v_mov_b32_e32 v118, v16
	v_mov_b32_e32 v119, v16
	v_mov_b32_e32 v124, v16
	v_mov_b32_e32 v125, v16
	v_mov_b32_e32 v126, v16
	v_mov_b32_e32 v127, v16
	v_mov_b32_e32 v136, v16
	v_mov_b32_e32 v137, v16
	v_mov_b32_e32 v138, v16
	v_mov_b32_e32 v139, v16
	v_mov_b32_e32 v140, v16
	v_mov_b32_e32 v141, v16
	v_mov_b32_e32 v142, v16
	v_mov_b32_e32 v143, v16
	v_mov_b32_e32 v112, v16
	v_mov_b32_e32 v113, v16
	v_mov_b32_e32 v114, v16
	v_mov_b32_e32 v115, v16
	v_mov_b32_e32 v120, v16
	v_mov_b32_e32 v121, v16
	v_mov_b32_e32 v122, v16
	v_mov_b32_e32 v123, v16
	v_mov_b32_e32 v128, v16
	v_mov_b32_e32 v129, v16
	v_mov_b32_e32 v130, v16
	v_mov_b32_e32 v131, v16
	v_mov_b32_e32 v132, v16
	v_mov_b32_e32 v133, v16
	v_mov_b32_e32 v134, v16
	v_mov_b32_e32 v135, v16
	v_mov_b32_e32 v144, v16
	v_mov_b32_e32 v145, v16
	v_mov_b32_e32 v146, v16
	v_mov_b32_e32 v147, v16
	v_mov_b32_e32 v148, v16
	v_mov_b32_e32 v149, v16
	v_mov_b32_e32 v150, v16
	v_mov_b32_e32 v151, v16
	v_mov_b32_e32 v152, v16
	v_mov_b32_e32 v153, v16
	v_mov_b32_e32 v154, v16
	v_mov_b32_e32 v155, v16
	v_mov_b32_e32 v156, v16
	v_mov_b32_e32 v157, v16
	v_mov_b32_e32 v158, v16
	v_mov_b32_e32 v159, v16
	s_waitcnt lgkmcnt(0)
	s_barrier

; #define G_LOAD(kt_) do { \
;     if constexpr (AF32) { _Pragma("unroll") for (int i = 0; i < 4; ++i) ld16_sc1(ra[i], Af + (size_t)i * 32 * lda + (kt_) * 32); } \
;     else { _Pragma("unroll") for (int i = 0; i < 2; ++i) ld16_sc1(rab[i], Ab + (size_t)i * 64 * lda + (kt_) * 32); } \
;     _Pragma("unroll") for (int i = 0; i < 4; ++i) ld16_sc1(rb[i], Bp + (size_t)(kt_) * bstep + i * 2048); } while (0)
; template <bool AF32, class Epi>
; __device__ __forceinline__ void gemm_tile(unsigned char* smem, const void* Ap, int lda, const bf16_t* WT, int N, int K, const Epi& epi, int m0, int n0,
;                                           GPre& pr, bool preloaded, const void* nAp, int nn0, bool has_next) {
;     ...
;   const bf16_t* Ab = (const bf16_t*)Ap + (size_t)(tid >> 2) * lda + (tid & 3) * 8;
;   const bf16_t* Bp = WT + (size_t)n0 * 32 + tid * 8;
;   const size_t bstep = (size_t)N * 32;
;   const int awf = (tid >> 3) * GLD + (tid & 7) * 4;
;   const int awb = (tid >> 2) * GLD + (tid & 3) * 8;
;     ...
;   if (!preloaded) G_LOAD(0);
;   G_STORE(0);
;   if (nk > 1) G_LOAD(1);
;   __syncthreads();
;   for (int kt = 0; kt < nk; ++kt) {
;     const int cur = kt & 1;
;     if (kt + 1 < nk) G_STORE(cur ^ 1);
;     if (kt + 2 < nk) G_LOAD(kt + 2);
;     const bf16_t* a_s = sbase + cur * G_STAGE + (wr * 64 + l15) * GLD + quad * 8;
;     const bf16_t* b_s = sbase + cur * G_STAGE + 128 * GLD + (wc * 128 + l15) * GLD + quad * 8;
.LBB0_428:
	s_nop 0
	s_waitcnt vmcnt(0)
	v_mul_lo_u32 v32, v29, 40
	v_add_lshl_u32 v155, v32, v30, 1
	v_lshrrev_b32_e32 v250, 2, v210
	v_add_u32_e32 v251, 4, v250
	v_and_b32_e32 v251, 8, v251
	v_and_b32_e32 v252, 3, v210
	v_lshlrev_b32_e32 v252, 3, v252
	v_xor_b32_e32 v252, v252, v251
	v_mad_u32_u24 v155, v250, 40, v252
	v_lshlrev_b32_e32 v155, 1, v155
	s_ashr_i32 s3, s70, 1
	v_and_b32_e32 v31, 15, v28
	ds_write_b128 v155, v[0:3]
	ds_write_b128 v155, v[4:7] offset:5120
	ds_write_b128 v155, v[8:11] offset:10240
	ds_write_b128 v155, v[12:15] offset:15360
	ds_write_b128 v155, v[16:19] offset:20480
	ds_write_b128 v155, v[20:23] offset:25600
	v_lshl_add_u64 v[0:1], v[24:25], 0, 64
	s_andn2_b32 s3, s3, 63
	global_load_dwordx4 v[0:3], v[0:1], off sc1
	v_lshl_add_u64 v[4:5], v[24:25], 0, s[20:21]
	v_or_b32_e32 v154, s3, v31
	s_lshl_b32 s3, s70, 1
	global_load_dwordx4 v[4:7], v[4:5], off sc1
	v_lshl_add_u64 v[8:9], v[26:27], 0, s[22:23]
	s_and_b32 s51, s3, 0x80
	global_load_dwordx4 v[8:11], v[8:9], off sc1
	v_lshl_add_u64 v[12:13], v[26:27], 0, s[24:25]
	v_or_b32_e32 v24, s51, v31
	global_load_dwordx4 v[12:15], v[12:13], off sc1
	v_lshl_add_u64 v[16:17], v[26:27], 0, s[26:27]
	v_lshl_add_u64 v[20:21], v[26:27], 0, s[28:29]
	v_mul_u32_u24_e32 v165, 0x50, v24
	v_mov_b64_e32 v[24:25], s[52:53]
	v_and_b32_e32 v26, 3, v28
	s_ashr_i32 s47, s46, 31
	global_load_dwordx4 v[16:19], v[16:17], off sc1
	v_mad_i64_i32 v[24:25], s[52:53], v29, s66, v[24:25]
	v_lshlrev_b32_e32 v26, 4, v26
	v_mov_b32_e32 v27, v153
	v_bfe_u32 v164, v28, 4, 2
	global_load_dwordx4 v[20:23], v[20:21], off sc1
	s_add_u32 s54, s63, s54
	v_lshl_add_u64 v[24:25], v[24:25], 0, v[26:27]
	v_lshlrev_b32_e32 v30, 3, v164
	s_addc_u32 s55, s64, s55
	v_lshl_add_u64 v[162:163], s[10:11], 0, v[24:25]
	v_mov_b32_e32 v24, 0
	v_mul_lo_u32 v166, v154, s65
	v_lshl_add_u64 v[160:161], v[156:157], 1, s[54:55]
	s_mov_b32 s52, 0
	v_lshlrev_b32_e32 v167, 1, v30
	v_add_u32_e32 v250, 4, v210
	v_and_b32_e32 v250, 8, v250
	v_lshlrev_b32_e32 v250, 1, v250
	v_xor_b32_e32 v167, v167, v250
	v_mov_b32_e32 v25, v24
	v_mov_b32_e32 v26, v24
	v_mov_b32_e32 v27, v24
	v_mov_b32_e32 v28, v24
	v_mov_b32_e32 v29, v24
	v_mov_b32_e32 v30, v24
	v_mov_b32_e32 v31, v24
	v_mov_b32_e32 v32, v24
	v_mov_b32_e32 v33, v24
	v_mov_b32_e32 v34, v24
	v_mov_b32_e32 v35, v24
	v_mov_b32_e32 v36, v24
	v_mov_b32_e32 v37, v24
	v_mov_b32_e32 v38, v24
	v_mov_b32_e32 v39, v24
	v_mov_b32_e32 v44, v24
	v_mov_b32_e32 v45, v24
	v_mov_b32_e32 v46, v24
	v_mov_b32_e32 v47, v24
	v_mov_b32_e32 v52, v24
	v_mov_b32_e32 v53, v24
	v_mov_b32_e32 v54, v24
	v_mov_b32_e32 v55, v24
	v_mov_b32_e32 v60, v24
	v_mov_b32_e32 v61, v24
	v_mov_b32_e32 v62, v24
	v_mov_b32_e32 v63, v24
	v_mov_b32_e32 v68, v24
	v_mov_b32_e32 v69, v24
	v_mov_b32_e32 v70, v24
	v_mov_b32_e32 v71, v24
	v_mov_b32_e32 v40, v24
	v_mov_b32_e32 v41, v24
	v_mov_b32_e32 v42, v24
	v_mov_b32_e32 v43, v24
	v_mov_b32_e32 v48, v24
	v_mov_b32_e32 v49, v24
	v_mov_b32_e32 v50, v24
	v_mov_b32_e32 v51, v24
	v_mov_b32_e32 v56, v24
	v_mov_b32_e32 v57, v24
	v_mov_b32_e32 v58, v24
	v_mov_b32_e32 v59, v24
	v_mov_b32_e32 v64, v24
	v_mov_b32_e32 v65, v24
	v_mov_b32_e32 v66, v24
	v_mov_b32_e32 v67, v24
	v_mov_b32_e32 v76, v24
	v_mov_b32_e32 v77, v24
	v_mov_b32_e32 v78, v24
	v_mov_b32_e32 v79, v24
	v_mov_b32_e32 v84, v24
	v_mov_b32_e32 v85, v24
	v_mov_b32_e32 v86, v24
	v_mov_b32_e32 v87, v24
	v_mov_b32_e32 v92, v24
	v_mov_b32_e32 v93, v24
	v_mov_b32_e32 v94, v24
	v_mov_b32_e32 v95, v24
	v_mov_b32_e32 v100, v24
	v_mov_b32_e32 v101, v24
	v_mov_b32_e32 v102, v24
	v_mov_b32_e32 v103, v24
	v_mov_b32_e32 v72, v24
	v_mov_b32_e32 v73, v24
	v_mov_b32_e32 v74, v24
	v_mov_b32_e32 v75, v24
	v_mov_b32_e32 v80, v24
	v_mov_b32_e32 v81, v24
	v_mov_b32_e32 v82, v24
	v_mov_b32_e32 v83, v24
	v_mov_b32_e32 v88, v24
	v_mov_b32_e32 v89, v24
	v_mov_b32_e32 v90, v24
	v_mov_b32_e32 v91, v24
	v_mov_b32_e32 v96, v24
	v_mov_b32_e32 v97, v24
	v_mov_b32_e32 v98, v24
	v_mov_b32_e32 v99, v24
	v_mov_b32_e32 v108, v24
	v_mov_b32_e32 v109, v24
	v_mov_b32_e32 v110, v24
	v_mov_b32_e32 v111, v24
	v_mov_b32_e32 v116, v24
	v_mov_b32_e32 v117, v24
	v_mov_b32_e32 v118, v24
	v_mov_b32_e32 v119, v24
	v_mov_b32_e32 v128, v24
	v_mov_b32_e32 v129, v24
	v_mov_b32_e32 v130, v24
	v_mov_b32_e32 v131, v24
	v_mov_b32_e32 v132, v24
	v_mov_b32_e32 v133, v24
	v_mov_b32_e32 v134, v24
	v_mov_b32_e32 v135, v24
	v_mov_b32_e32 v104, v24
	v_mov_b32_e32 v105, v24
	v_mov_b32_e32 v106, v24
	v_mov_b32_e32 v107, v24
	v_mov_b32_e32 v112, v24
	v_mov_b32_e32 v113, v24
	v_mov_b32_e32 v114, v24
	v_mov_b32_e32 v115, v24
	v_mov_b32_e32 v120, v24
	v_mov_b32_e32 v121, v24
	v_mov_b32_e32 v122, v24
	v_mov_b32_e32 v123, v24
	v_mov_b32_e32 v124, v24
	v_mov_b32_e32 v125, v24
	v_mov_b32_e32 v126, v24
	v_mov_b32_e32 v127, v24
	v_mov_b32_e32 v136, v24
	v_mov_b32_e32 v137, v24
	v_mov_b32_e32 v138, v24
	v_mov_b32_e32 v139, v24
	v_mov_b32_e32 v140, v24
	v_mov_b32_e32 v141, v24
	v_mov_b32_e32 v142, v24
	v_mov_b32_e32 v143, v24
	v_mov_b32_e32 v144, v24
	v_mov_b32_e32 v145, v24
	v_mov_b32_e32 v146, v24
	v_mov_b32_e32 v147, v24
	v_mov_b32_e32 v148, v24
	v_mov_b32_e32 v149, v24
	v_mov_b32_e32 v150, v24
	v_mov_b32_e32 v151, v24
	s_waitcnt lgkmcnt(0)
	s_barrier

; #define G_LOAD(kt_) do { \
;     if constexpr (AF32) { _Pragma("unroll") for (int i = 0; i < 4; ++i) ld16_sc1(ra[i], Af + (size_t)i * 32 * lda + (kt_) * 32); } \
;     else { _Pragma("unroll") for (int i = 0; i < 2; ++i) ld16_sc1(rab[i], Ab + (size_t)i * 64 * lda + (kt_) * 32); } \
;     _Pragma("unroll") for (int i = 0; i < 4; ++i) ld16_sc1(rb[i], Bp + (size_t)(kt_) * bstep + i * 2048); } while (0)
; template <bool AF32, class Epi>
; __device__ __forceinline__ void gemm_tile(unsigned char* smem, const void* Ap, int lda, const bf16_t* WT, int N, int K, const Epi& epi, int m0, int n0,
;                                           GPre& pr, bool preloaded, const void* nAp, int nn0, bool has_next) {
;     ...
;   const float* Af = (const float*)Ap + (size_t)(tid >> 3) * lda + (tid & 7) * 4;
;   const bf16_t* Ab = (const bf16_t*)Ap + (size_t)(tid >> 2) * lda + (tid & 3) * 8;
;   const bf16_t* Bp = WT + (size_t)n0 * 32 + tid * 8;
;   const size_t bstep = (size_t)N * 32;
;   const int awf = (tid >> 3) * GLD + (tid & 7) * 4;
;   const int awb = (tid >> 2) * GLD + (tid & 3) * 8;
;     ...
;   if (!preloaded) G_LOAD(0);
;   G_STORE(0);
;   if (nk > 1) G_LOAD(1);
;   __syncthreads();
;   for (int kt = 0; kt < nk; ++kt) {
;     const int cur = kt & 1;
;     if (kt + 1 < nk) G_STORE(cur ^ 1);
;     if (kt + 2 < nk) G_LOAD(kt + 2);
;     const bf16_t* a_s = sbase + cur * G_STAGE + (wr * 64 + l15) * GLD + quad * 8;
;     const bf16_t* b_s = sbase + cur * G_STAGE + 128 * GLD + (wc * 128 + l15) * GLD + quad * 8;
.LBB0_459:
	v_and_b32_e32 v52, 15, v18
	v_bfe_u32 v53, v18, 4, 2
	v_lshrrev_b32_e32 v19, 2, v18
	v_and_b32_e32 v18, 24, v184
	s_waitcnt vmcnt(0)
	v_mad_u64_u32 v[162:163], s[70:71], v19, 40, v[18:19]
	v_lshrrev_b32_e32 v250, 2, v210
	v_add_u32_e32 v251, 4, v250
	v_and_b32_e32 v251, 8, v251
	v_and_b32_e32 v252, 3, v210
	v_lshlrev_b32_e32 v252, 3, v252
	v_xor_b32_e32 v252, v252, v251
	v_mad_u32_u24 v162, v250, 40, v252
	v_cvt_pk_bf16_f32 v18, v40, v41
	v_mov_b32_e32 v21, v40
	v_mov_b32_e32 v40, v45
	v_mov_b32_e32 v20, v44
	v_pk_mul_f32 v[22:23], v[40:41], v[40:41]
	v_lshlrev_b32_e32 v190, 2, v179
	v_pk_fma_f32 v[20:21], v[20:21], v[20:21], v[22:23]
	v_mov_b32_e32 v22, v46
	v_mov_b32_e32 v23, v42
	v_mad_u64_u32 v[160:161], s[70:71], v180, 40, v[190:191]
	v_lshrrev_b32_e32 v250, 3, v210
	v_add_u32_e32 v251, 4, v250
	v_and_b32_e32 v251, 8, v251
	v_and_b32_e32 v252, 7, v210
	v_lshlrev_b32_e32 v252, 2, v252
	v_xor_b32_e32 v252, v252, v251
	v_mad_u32_u24 v160, v250, 40, v252
	v_cvt_pk_bf16_f32 v19, v42, v43
	v_pk_fma_f32 v[20:21], v[22:23], v[22:23], v[20:21]
	v_mov_b32_e32 v42, v47
	v_lshlrev_b32_e32 v161, 1, v160
	v_pk_fma_f32 v[186:187], v[42:43], v[42:43], v[20:21]
	v_cvt_pk_bf16_f32 v20, v44, v45
	v_cvt_pk_bf16_f32 v21, v46, v47
	ds_write2st64_b64 v161, v[18:19], v[20:21] offset1:5
	v_cvt_pk_bf16_f32 v18, v32, v33
	v_mov_b32_e32 v21, v32
	v_mov_b32_e32 v32, v37
	v_mov_b32_e32 v20, v36
	v_pk_mul_f32 v[22:23], v[32:33], v[32:33]
	v_cvt_pk_bf16_f32 v19, v34, v35
	v_pk_fma_f32 v[20:21], v[20:21], v[20:21], v[22:23]
	v_mov_b32_e32 v22, v38
	v_mov_b32_e32 v23, v34
	v_pk_fma_f32 v[20:21], v[22:23], v[22:23], v[20:21]
	v_mov_b32_e32 v34, v39
	v_pk_fma_f32 v[182:183], v[34:35], v[34:35], v[20:21]
	v_cvt_pk_bf16_f32 v20, v36, v37
	v_cvt_pk_bf16_f32 v21, v38, v39
	v_lshlrev_b32_e32 v163, 1, v162
	ds_write2st64_b64 v161, v[18:19], v[20:21] offset0:10 offset1:15
	ds_write_b128 v163, v[0:3] offset:10240
	ds_write_b128 v163, v[4:7] offset:15360
	ds_write_b128 v163, v[8:11] offset:20480
	ds_write_b128 v163, v[12:15] offset:25600
	v_lshl_add_u64 v[0:1], v[16:17], 0, s[28:29]
	global_load_dwordx4 v[28:31], v[0:1], off sc1
	v_lshl_add_u64 v[0:1], v[16:17], 0, s[30:31]
	global_load_dwordx4 v[24:27], v[0:1], off sc1
	v_lshl_add_u64 v[0:1], v[16:17], 0, s[34:35]
	s_ashr_i32 s3, s49, 1
	global_load_dwordx4 v[20:23], v[0:1], off sc1
	v_lshl_add_u64 v[0:1], v[16:17], 0, s[36:37]
	s_andn2_b32 s3, s3, 63
	v_lshlrev_b64 v[188:189], 10, v[180:181]
	global_load_dwordx4 v[16:19], v[0:1], off sc1
	v_lshl_add_u64 v[0:1], v[50:51], 0, s[38:39]
	v_or_b32_e32 v181, s3, v52
	s_lshl_b32 s3, s49, 1
	global_load_dwordx4 v[0:3], v[0:1], off sc1
	v_lshl_add_u64 v[4:5], v[50:51], 0, s[40:41]
	s_and_b32 s49, s3, 0x80
	global_load_dwordx4 v[4:7], v[4:5], off sc1
	v_lshl_add_u64 v[8:9], v[50:51], 0, s[42:43]
	v_or_b32_e32 v32, s49, v52
	global_load_dwordx4 v[8:11], v[8:9], off sc1
	v_lshl_add_u64 v[12:13], v[50:51], 0, s[44:45]
	v_mul_u32_u24_e32 v168, 0x50, v32
	v_lshl_add_u64 v[32:33], s[54:55], 0, v[48:49]
	global_load_dwordx4 v[12:15], v[12:13], off sc1
	s_add_u32 s56, s63, s56
	v_lshl_add_u64 v[32:33], v[32:33], 0, v[176:177]
	v_lshlrev_b32_e32 v178, 3, v53
	s_addc_u32 s57, s64, s57
	v_lshl_add_u64 v[166:167], s[14:15], 0, v[32:33]
	v_mov_b32_e32 v32, 0
	v_mul_lo_u32 v169, v181, s65
	v_lshl_add_u64 v[164:165], v[184:185], 1, s[56:57]
	s_mov_b32 s51, 0
	v_lshlrev_b32_e32 v170, 1, v178
	v_add_u32_e32 v250, 4, v210
	v_and_b32_e32 v250, 8, v250
	v_lshlrev_b32_e32 v250, 1, v250
	v_xor_b32_e32 v170, v170, v250
	v_mov_b32_e32 v33, v32
	v_mov_b32_e32 v34, v32
	v_mov_b32_e32 v35, v32
	v_mov_b32_e32 v36, v32
	v_mov_b32_e32 v37, v32
	v_mov_b32_e32 v38, v32
	v_mov_b32_e32 v39, v32
	v_mov_b32_e32 v40, v32
	v_mov_b32_e32 v41, v32
	v_mov_b32_e32 v42, v32
	v_mov_b32_e32 v43, v32
	v_mov_b32_e32 v44, v32
	v_mov_b32_e32 v45, v32
	v_mov_b32_e32 v46, v32
	v_mov_b32_e32 v47, v32
	v_mov_b32_e32 v52, v32
	v_mov_b32_e32 v53, v32
	v_mov_b32_e32 v54, v32
	v_mov_b32_e32 v55, v32
	v_mov_b32_e32 v60, v32
	v_mov_b32_e32 v61, v32
	v_mov_b32_e32 v62, v32
	v_mov_b32_e32 v63, v32
	v_mov_b32_e32 v68, v32
	v_mov_b32_e32 v69, v32
	v_mov_b32_e32 v70, v32
	v_mov_b32_e32 v71, v32
	v_mov_b32_e32 v76, v32
	v_mov_b32_e32 v77, v32
	v_mov_b32_e32 v78, v32
	v_mov_b32_e32 v79, v32
	v_mov_b32_e32 v48, v32
	v_mov_b32_e32 v49, v32
	v_mov_b32_e32 v50, v32
	v_mov_b32_e32 v51, v32
	v_mov_b32_e32 v56, v32
	v_mov_b32_e32 v57, v32
	v_mov_b32_e32 v58, v32
	v_mov_b32_e32 v59, v32
	v_mov_b32_e32 v64, v32
	v_mov_b32_e32 v65, v32
	v_mov_b32_e32 v66, v32
	v_mov_b32_e32 v67, v32
	v_mov_b32_e32 v72, v32
	v_mov_b32_e32 v73, v32
	v_mov_b32_e32 v74, v32
	v_mov_b32_e32 v75, v32
	v_mov_b32_e32 v84, v32
	v_mov_b32_e32 v85, v32
	v_mov_b32_e32 v86, v32
	v_mov_b32_e32 v87, v32
	v_mov_b32_e32 v92, v32
	v_mov_b32_e32 v93, v32
	v_mov_b32_e32 v94, v32
	v_mov_b32_e32 v95, v32
	v_mov_b32_e32 v100, v32
	v_mov_b32_e32 v101, v32
	v_mov_b32_e32 v102, v32
	v_mov_b32_e32 v103, v32
	v_mov_b32_e32 v108, v32
	v_mov_b32_e32 v109, v32
	v_mov_b32_e32 v110, v32
	v_mov_b32_e32 v111, v32
	v_mov_b32_e32 v80, v32
	v_mov_b32_e32 v81, v32
	v_mov_b32_e32 v82, v32
	v_mov_b32_e32 v83, v32
	v_mov_b32_e32 v88, v32
	v_mov_b32_e32 v89, v32
	v_mov_b32_e32 v90, v32
	v_mov_b32_e32 v91, v32
	v_mov_b32_e32 v96, v32
	v_mov_b32_e32 v97, v32
	v_mov_b32_e32 v98, v32
	v_mov_b32_e32 v99, v32
	v_mov_b32_e32 v104, v32
	v_mov_b32_e32 v105, v32
	v_mov_b32_e32 v106, v32
	v_mov_b32_e32 v107, v32
	v_mov_b32_e32 v116, v32
	v_mov_b32_e32 v117, v32
	v_mov_b32_e32 v118, v32
	v_mov_b32_e32 v119, v32
	v_mov_b32_e32 v124, v32
	v_mov_b32_e32 v125, v32
	v_mov_b32_e32 v126, v32
	v_mov_b32_e32 v127, v32
	v_mov_b32_e32 v136, v32
	v_mov_b32_e32 v137, v32
	v_mov_b32_e32 v138, v32
	v_mov_b32_e32 v139, v32
	v_mov_b32_e32 v140, v32
	v_mov_b32_e32 v141, v32
	v_mov_b32_e32 v142, v32
	v_mov_b32_e32 v143, v32
	v_mov_b32_e32 v112, v32
	v_mov_b32_e32 v113, v32
	v_mov_b32_e32 v114, v32
	v_mov_b32_e32 v115, v32
	v_mov_b32_e32 v120, v32
	v_mov_b32_e32 v121, v32
	v_mov_b32_e32 v122, v32
	v_mov_b32_e32 v123, v32
	v_mov_b32_e32 v128, v32
	v_mov_b32_e32 v129, v32
	v_mov_b32_e32 v130, v32
	v_mov_b32_e32 v131, v32
	v_mov_b32_e32 v132, v32
	v_mov_b32_e32 v133, v32
	v_mov_b32_e32 v134, v32
	v_mov_b32_e32 v135, v32
	v_mov_b32_e32 v144, v32
	v_mov_b32_e32 v145, v32
	v_mov_b32_e32 v146, v32
	v_mov_b32_e32 v147, v32
	v_mov_b32_e32 v148, v32
	v_mov_b32_e32 v149, v32
	v_mov_b32_e32 v150, v32
	v_mov_b32_e32 v151, v32
	v_mov_b32_e32 v152, v32
	v_mov_b32_e32 v153, v32
	v_mov_b32_e32 v154, v32
	v_mov_b32_e32 v155, v32
	v_mov_b32_e32 v156, v32
	v_mov_b32_e32 v157, v32
	v_mov_b32_e32 v158, v32
	v_mov_b32_e32 v159, v32
	s_waitcnt lgkmcnt(0)
	s_barrier

; #define G_LOAD(kt_) do { \
;     if constexpr (AF32) { _Pragma("unroll") for (int i = 0; i < 4; ++i) ld16_sc1(ra[i], Af + (size_t)i * 32 * lda + (kt_) * 32); } \
;     else { _Pragma("unroll") for (int i = 0; i < 2; ++i) ld16_sc1(rab[i], Ab + (size_t)i * 64 * lda + (kt_) * 32); } \
;     _Pragma("unroll") for (int i = 0; i < 4; ++i) ld16_sc1(rb[i], Bp + (size_t)(kt_) * bstep + i * 2048); } while (0)
; template <bool AF32, class Epi>
; __device__ __forceinline__ void gemm_tile(unsigned char* smem, const void* Ap, int lda, const bf16_t* WT, int N, int K, const Epi& epi, int m0, int n0,
;                                           GPre& pr, bool preloaded, const void* nAp, int nn0, bool has_next) {
;     ...
;   const bf16_t* Ab = (const bf16_t*)Ap + (size_t)(tid >> 2) * lda + (tid & 3) * 8;
;   const bf16_t* Bp = WT + (size_t)n0 * 32 + tid * 8;
;   const size_t bstep = (size_t)N * 32;
;   const int awf = (tid >> 3) * GLD + (tid & 7) * 4;
;   const int awb = (tid >> 2) * GLD + (tid & 3) * 8;
;     ...
;   if (!preloaded) G_LOAD(0);
;   G_STORE(0);
;   if (nk > 1) G_LOAD(1);
;   __syncthreads();
;   for (int kt = 0; kt < nk; ++kt) {
;     const int cur = kt & 1;
;     if (kt + 1 < nk) G_STORE(cur ^ 1);
;     if (kt + 2 < nk) G_LOAD(kt + 2);
;     const bf16_t* a_s = sbase + cur * G_STAGE + (wr * 64 + l15) * GLD + quad * 8;
;     const bf16_t* b_s = sbase + cur * G_STAGE + 128 * GLD + (wc * 128 + l15) * GLD + quad * 8;
.LBB0_554:
	s_nop 0
	s_waitcnt vmcnt(0)
	v_mul_lo_u32 v32, v29, 40
	v_add_lshl_u32 v155, v32, v30, 1
	v_lshrrev_b32_e32 v250, 2, v210
	v_add_u32_e32 v251, 4, v250
	v_and_b32_e32 v251, 8, v251
	v_and_b32_e32 v252, 3, v210
	v_lshlrev_b32_e32 v252, 3, v252
	v_xor_b32_e32 v252, v252, v251
	v_mad_u32_u24 v155, v250, 40, v252
	v_lshlrev_b32_e32 v155, 1, v155
	s_ashr_i32 s3, s68, 1
	v_and_b32_e32 v31, 15, v28
	ds_write_b128 v155, v[0:3]
	ds_write_b128 v155, v[4:7] offset:5120
	ds_write_b128 v155, v[8:11] offset:10240
	ds_write_b128 v155, v[12:15] offset:15360
	ds_write_b128 v155, v[16:19] offset:20480
	ds_write_b128 v155, v[20:23] offset:25600
	v_lshl_add_u64 v[0:1], v[24:25], 0, 64
	s_andn2_b32 s3, s3, 63
	global_load_dwordx4 v[0:3], v[0:1], off sc1
	v_lshl_add_u64 v[4:5], v[24:25], 0, s[18:19]
	v_or_b32_e32 v154, s3, v31
	s_lshl_b32 s3, s68, 1
	global_load_dwordx4 v[4:7], v[4:5], off sc1
	v_lshl_add_u64 v[8:9], v[26:27], 0, s[20:21]
	s_and_b32 s49, s3, 0x80
	global_load_dwordx4 v[8:11], v[8:9], off sc1
	v_lshl_add_u64 v[12:13], v[26:27], 0, s[22:23]
	v_or_b32_e32 v24, s49, v31
	global_load_dwordx4 v[12:15], v[12:13], off sc1
	v_lshl_add_u64 v[16:17], v[26:27], 0, s[24:25]
	v_lshl_add_u64 v[20:21], v[26:27], 0, s[26:27]
	v_mul_u32_u24_e32 v165, 0x50, v24
	v_mov_b64_e32 v[24:25], s[50:51]
	v_and_b32_e32 v26, 3, v28
	s_ashr_i32 s45, s44, 31
	global_load_dwordx4 v[16:19], v[16:17], off sc1
	v_mad_i64_i32 v[24:25], s[50:51], v29, s64, v[24:25]
	v_lshlrev_b32_e32 v26, 4, v26
	v_mov_b32_e32 v27, v153
	v_bfe_u32 v164, v28, 4, 2
	global_load_dwordx4 v[20:23], v[20:21], off sc1
	s_add_u32 s52, s61, s52
	v_lshl_add_u64 v[24:25], v[24:25], 0, v[26:27]
	v_lshlrev_b32_e32 v30, 3, v164
	s_addc_u32 s53, s62, s53
	v_lshl_add_u64 v[162:163], s[8:9], 0, v[24:25]
	v_mov_b32_e32 v24, 0
	v_mul_lo_u32 v166, v154, s63
	v_lshl_add_u64 v[160:161], v[156:157], 1, s[52:53]
	s_mov_b32 s50, 0
	v_lshlrev_b32_e32 v167, 1, v30
	v_add_u32_e32 v250, 4, v210
	v_and_b32_e32 v250, 8, v250
	v_lshlrev_b32_e32 v250, 1, v250
	v_xor_b32_e32 v167, v167, v250
	v_mov_b32_e32 v25, v24
	v_mov_b32_e32 v26, v24
	v_mov_b32_e32 v27, v24
	v_mov_b32_e32 v28, v24
	v_mov_b32_e32 v29, v24
	v_mov_b32_e32 v30, v24
	v_mov_b32_e32 v31, v24
	v_mov_b32_e32 v32, v24
	v_mov_b32_e32 v33, v24
	v_mov_b32_e32 v34, v24
	v_mov_b32_e32 v35, v24
	v_mov_b32_e32 v36, v24
	v_mov_b32_e32 v37, v24
	v_mov_b32_e32 v38, v24
	v_mov_b32_e32 v39, v24
	v_mov_b32_e32 v44, v24
	v_mov_b32_e32 v45, v24
	v_mov_b32_e32 v46, v24
	v_mov_b32_e32 v47, v24
	v_mov_b32_e32 v52, v24
	v_mov_b32_e32 v53, v24
	v_mov_b32_e32 v54, v24
	v_mov_b32_e32 v55, v24
	v_mov_b32_e32 v60, v24
	v_mov_b32_e32 v61, v24
	v_mov_b32_e32 v62, v24
	v_mov_b32_e32 v63, v24
	v_mov_b32_e32 v68, v24
	v_mov_b32_e32 v69, v24
	v_mov_b32_e32 v70, v24
	v_mov_b32_e32 v71, v24
	v_mov_b32_e32 v40, v24
	v_mov_b32_e32 v41, v24
	v_mov_b32_e32 v42, v24
	v_mov_b32_e32 v43, v24
	v_mov_b32_e32 v48, v24
	v_mov_b32_e32 v49, v24
	v_mov_b32_e32 v50, v24
	v_mov_b32_e32 v51, v24
	v_mov_b32_e32 v56, v24
	v_mov_b32_e32 v57, v24
	v_mov_b32_e32 v58, v24
	v_mov_b32_e32 v59, v24
	v_mov_b32_e32 v64, v24
	v_mov_b32_e32 v65, v24
	v_mov_b32_e32 v66, v24
	v_mov_b32_e32 v67, v24
	v_mov_b32_e32 v76, v24
	v_mov_b32_e32 v77, v24
	v_mov_b32_e32 v78, v24
	v_mov_b32_e32 v79, v24
	v_mov_b32_e32 v84, v24
	v_mov_b32_e32 v85, v24
	v_mov_b32_e32 v86, v24
	v_mov_b32_e32 v87, v24
	v_mov_b32_e32 v92, v24
	v_mov_b32_e32 v93, v24
	v_mov_b32_e32 v94, v24
	v_mov_b32_e32 v95, v24
	v_mov_b32_e32 v100, v24
	v_mov_b32_e32 v101, v24
	v_mov_b32_e32 v102, v24
	v_mov_b32_e32 v103, v24
	v_mov_b32_e32 v72, v24
	v_mov_b32_e32 v73, v24
	v_mov_b32_e32 v74, v24
	v_mov_b32_e32 v75, v24
	v_mov_b32_e32 v80, v24
	v_mov_b32_e32 v81, v24
	v_mov_b32_e32 v82, v24
	v_mov_b32_e32 v83, v24
	v_mov_b32_e32 v88, v24
	v_mov_b32_e32 v89, v24
	v_mov_b32_e32 v90, v24
	v_mov_b32_e32 v91, v24
	v_mov_b32_e32 v96, v24
	v_mov_b32_e32 v97, v24
	v_mov_b32_e32 v98, v24
	v_mov_b32_e32 v99, v24
	v_mov_b32_e32 v108, v24
	v_mov_b32_e32 v109, v24
	v_mov_b32_e32 v110, v24
	v_mov_b32_e32 v111, v24
	v_mov_b32_e32 v116, v24
	v_mov_b32_e32 v117, v24
	v_mov_b32_e32 v118, v24
	v_mov_b32_e32 v119, v24
	v_mov_b32_e32 v128, v24
	v_mov_b32_e32 v129, v24
	v_mov_b32_e32 v130, v24
	v_mov_b32_e32 v131, v24
	v_mov_b32_e32 v132, v24
	v_mov_b32_e32 v133, v24
	v_mov_b32_e32 v134, v24
	v_mov_b32_e32 v135, v24
	v_mov_b32_e32 v104, v24
	v_mov_b32_e32 v105, v24
	v_mov_b32_e32 v106, v24
	v_mov_b32_e32 v107, v24
	v_mov_b32_e32 v112, v24
	v_mov_b32_e32 v113, v24
	v_mov_b32_e32 v114, v24
	v_mov_b32_e32 v115, v24
	v_mov_b32_e32 v120, v24
	v_mov_b32_e32 v121, v24
	v_mov_b32_e32 v122, v24
	v_mov_b32_e32 v123, v24
	v_mov_b32_e32 v124, v24
	v_mov_b32_e32 v125, v24
	v_mov_b32_e32 v126, v24
	v_mov_b32_e32 v127, v24
	v_mov_b32_e32 v136, v24
	v_mov_b32_e32 v137, v24
	v_mov_b32_e32 v138, v24
	v_mov_b32_e32 v139, v24
	v_mov_b32_e32 v140, v24
	v_mov_b32_e32 v141, v24
	v_mov_b32_e32 v142, v24
	v_mov_b32_e32 v143, v24
	v_mov_b32_e32 v144, v24
	v_mov_b32_e32 v145, v24
	v_mov_b32_e32 v146, v24
	v_mov_b32_e32 v147, v24
	v_mov_b32_e32 v148, v24
	v_mov_b32_e32 v149, v24
	v_mov_b32_e32 v150, v24
	v_mov_b32_e32 v151, v24
	s_waitcnt lgkmcnt(0)
	s_barrier

; #define G_LOAD(kt_) do { \
;     if constexpr (AF32) { _Pragma("unroll") for (int i = 0; i < 4; ++i) ld16_sc1(ra[i], Af + (size_t)i * 32 * lda + (kt_) * 32); } \
;     else { _Pragma("unroll") for (int i = 0; i < 2; ++i) ld16_sc1(rab[i], Ab + (size_t)i * 64 * lda + (kt_) * 32); } \
;     _Pragma("unroll") for (int i = 0; i < 4; ++i) ld16_sc1(rb[i], Bp + (size_t)(kt_) * bstep + i * 2048); } while (0)
; template <bool AF32, class Epi>
; __device__ __forceinline__ void gemm_tile(unsigned char* smem, const void* Ap, int lda, const bf16_t* WT, int N, int K, const Epi& epi, int m0, int n0,
;                                           GPre& pr, bool preloaded, const void* nAp, int nn0, bool has_next) {
;     ...
;   const bf16_t* Ab = (const bf16_t*)Ap + (size_t)(tid >> 2) * lda + (tid & 3) * 8;
;   const bf16_t* Bp = WT + (size_t)n0 * 32 + tid * 8;
;   const size_t bstep = (size_t)N * 32;
;   const int awf = (tid >> 3) * GLD + (tid & 7) * 4;
;   const int awb = (tid >> 2) * GLD + (tid & 3) * 8;
;     ...
;   if (!preloaded) G_LOAD(0);
;   G_STORE(0);
;   if (nk > 1) G_LOAD(1);
;   __syncthreads();
;   for (int kt = 0; kt < nk; ++kt) {
;     const int cur = kt & 1;
;     if (kt + 1 < nk) G_STORE(cur ^ 1);
;     if (kt + 2 < nk) G_LOAD(kt + 2);
;     const bf16_t* a_s = sbase + cur * G_STAGE + (wr * 64 + l15) * GLD + quad * 8;
;     const bf16_t* b_s = sbase + cur * G_STAGE + 128 * GLD + (wc * 128 + l15) * GLD + quad * 8;
.LBB0_646:
	s_nop 0
	s_waitcnt vmcnt(0)
	v_lshlrev_b64 v[158:159], 10, v[30:31]
	v_mul_lo_u32 v30, v30, 40
	v_add_lshl_u32 v155, v30, v33, 1
	v_lshrrev_b32_e32 v250, 2, v210
	v_add_u32_e32 v251, 4, v250
	v_and_b32_e32 v251, 8, v251
	v_and_b32_e32 v252, 3, v210
	v_lshlrev_b32_e32 v252, 3, v252
	v_xor_b32_e32 v252, v252, v251
	v_mad_u32_u24 v155, v250, 40, v252
	v_lshlrev_b32_e32 v155, 1, v155
	s_ashr_i32 s3, s51, 1
	v_and_b32_e32 v31, 15, v32
	ds_write_b128 v155, v[0:3]
	ds_write_b128 v155, v[4:7] offset:5120
	ds_write_b128 v155, v[8:11] offset:10240
	ds_write_b128 v155, v[12:15] offset:15360
	ds_write_b128 v155, v[16:19] offset:20480
	ds_write_b128 v155, v[20:23] offset:25600
	v_lshl_add_u64 v[0:1], v[26:27], 0, 64
	s_andn2_b32 s3, s3, 63
	global_load_dwordx4 v[0:3], v[0:1], off sc1
	v_lshl_add_u64 v[4:5], v[26:27], 0, s[18:19]
	v_or_b32_e32 v154, s3, v31
	s_lshl_b32 s3, s51, 1
	global_load_dwordx4 v[4:7], v[4:5], off sc1
	v_lshl_add_u64 v[8:9], v[28:29], 0, s[20:21]
	s_and_b32 s49, s3, 0x80
	global_load_dwordx4 v[8:11], v[8:9], off sc1
	v_lshl_add_u64 v[12:13], v[28:29], 0, s[22:23]
	v_or_b32_e32 v26, s49, v31
	global_load_dwordx4 v[12:15], v[12:13], off sc1
	v_lshl_add_u64 v[16:17], v[28:29], 0, s[24:25]
	v_mul_u32_u24_e32 v165, 0x50, v26
	v_and_b32_e32 v26, 3, v32
	global_load_dwordx4 v[16:19], v[16:17], off sc1
	v_lshl_add_u64 v[20:21], v[28:29], 0, s[26:27]
	v_lshl_add_u64 v[24:25], s[52:53], 0, v[24:25]
	v_lshlrev_b32_e32 v26, 4, v26
	v_mov_b32_e32 v27, v153
	v_bfe_u32 v164, v32, 4, 2
	global_load_dwordx4 v[20:23], v[20:21], off sc1
	s_add_u32 s54, s62, s54
	v_lshl_add_u64 v[24:25], v[24:25], 0, v[26:27]
	v_lshlrev_b32_e32 v28, 3, v164
	s_addc_u32 s55, s63, s55
	v_lshl_add_u64 v[162:163], s[8:9], 0, v[24:25]
	v_mov_b32_e32 v24, 0
	v_mul_lo_u32 v166, v154, s64
	v_lshl_add_u64 v[160:161], v[156:157], 1, s[54:55]
	s_mov_b32 s51, 0
	v_lshlrev_b32_e32 v167, 1, v28
	v_add_u32_e32 v250, 4, v210
	v_and_b32_e32 v250, 8, v250
	v_lshlrev_b32_e32 v250, 1, v250
	v_xor_b32_e32 v167, v167, v250
	v_mov_b32_e32 v25, v24
	v_mov_b32_e32 v26, v24
	v_mov_b32_e32 v27, v24
	v_mov_b32_e32 v28, v24
	v_mov_b32_e32 v29, v24
	v_mov_b32_e32 v30, v24
	v_mov_b32_e32 v31, v24
	v_mov_b32_e32 v32, v24
	v_mov_b32_e32 v33, v24
	v_mov_b32_e32 v34, v24
	v_mov_b32_e32 v35, v24
	v_mov_b32_e32 v36, v24
	v_mov_b32_e32 v37, v24
	v_mov_b32_e32 v38, v24
	v_mov_b32_e32 v39, v24
	v_mov_b32_e32 v44, v24
	v_mov_b32_e32 v45, v24
	v_mov_b32_e32 v46, v24
	v_mov_b32_e32 v47, v24
	v_mov_b32_e32 v52, v24
	v_mov_b32_e32 v53, v24
	v_mov_b32_e32 v54, v24
	v_mov_b32_e32 v55, v24
	v_mov_b32_e32 v60, v24
	v_mov_b32_e32 v61, v24
	v_mov_b32_e32 v62, v24
	v_mov_b32_e32 v63, v24
	v_mov_b32_e32 v68, v24
	v_mov_b32_e32 v69, v24
	v_mov_b32_e32 v70, v24
	v_mov_b32_e32 v71, v24
	v_mov_b32_e32 v40, v24
	v_mov_b32_e32 v41, v24
	v_mov_b32_e32 v42, v24
	v_mov_b32_e32 v43, v24
	v_mov_b32_e32 v48, v24
	v_mov_b32_e32 v49, v24
	v_mov_b32_e32 v50, v24
	v_mov_b32_e32 v51, v24
	v_mov_b32_e32 v56, v24
	v_mov_b32_e32 v57, v24
	v_mov_b32_e32 v58, v24
	v_mov_b32_e32 v59, v24
	v_mov_b32_e32 v64, v24
	v_mov_b32_e32 v65, v24
	v_mov_b32_e32 v66, v24
	v_mov_b32_e32 v67, v24
	v_mov_b32_e32 v76, v24
	v_mov_b32_e32 v77, v24
	v_mov_b32_e32 v78, v24
	v_mov_b32_e32 v79, v24
	v_mov_b32_e32 v84, v24
	v_mov_b32_e32 v85, v24
	v_mov_b32_e32 v86, v24
	v_mov_b32_e32 v87, v24
	v_mov_b32_e32 v92, v24
	v_mov_b32_e32 v93, v24
	v_mov_b32_e32 v94, v24
	v_mov_b32_e32 v95, v24
	v_mov_b32_e32 v100, v24
	v_mov_b32_e32 v101, v24
	v_mov_b32_e32 v102, v24
	v_mov_b32_e32 v103, v24
	v_mov_b32_e32 v72, v24
	v_mov_b32_e32 v73, v24
	v_mov_b32_e32 v74, v24
	v_mov_b32_e32 v75, v24
	v_mov_b32_e32 v80, v24
	v_mov_b32_e32 v81, v24
	v_mov_b32_e32 v82, v24
	v_mov_b32_e32 v83, v24
	v_mov_b32_e32 v88, v24
	v_mov_b32_e32 v89, v24
	v_mov_b32_e32 v90, v24
	v_mov_b32_e32 v91, v24
	v_mov_b32_e32 v96, v24
	v_mov_b32_e32 v97, v24
	v_mov_b32_e32 v98, v24
	v_mov_b32_e32 v99, v24
	v_mov_b32_e32 v108, v24
	v_mov_b32_e32 v109, v24
	v_mov_b32_e32 v110, v24
	v_mov_b32_e32 v111, v24
	v_mov_b32_e32 v116, v24
	v_mov_b32_e32 v117, v24
	v_mov_b32_e32 v118, v24
	v_mov_b32_e32 v119, v24
	v_mov_b32_e32 v128, v24
	v_mov_b32_e32 v129, v24
	v_mov_b32_e32 v130, v24
	v_mov_b32_e32 v131, v24
	v_mov_b32_e32 v132, v24
	v_mov_b32_e32 v133, v24
	v_mov_b32_e32 v134, v24
	v_mov_b32_e32 v135, v24
	v_mov_b32_e32 v104, v24
	v_mov_b32_e32 v105, v24
	v_mov_b32_e32 v106, v24
	v_mov_b32_e32 v107, v24
	v_mov_b32_e32 v112, v24
	v_mov_b32_e32 v113, v24
	v_mov_b32_e32 v114, v24
	v_mov_b32_e32 v115, v24
	v_mov_b32_e32 v120, v24
	v_mov_b32_e32 v121, v24
	v_mov_b32_e32 v122, v24
	v_mov_b32_e32 v123, v24
	v_mov_b32_e32 v124, v24
	v_mov_b32_e32 v125, v24
	v_mov_b32_e32 v126, v24
	v_mov_b32_e32 v127, v24
	v_mov_b32_e32 v136, v24
	v_mov_b32_e32 v137, v24
	v_mov_b32_e32 v138, v24
	v_mov_b32_e32 v139, v24
	v_mov_b32_e32 v140, v24
	v_mov_b32_e32 v141, v24
	v_mov_b32_e32 v142, v24
	v_mov_b32_e32 v143, v24
	v_mov_b32_e32 v144, v24
	v_mov_b32_e32 v145, v24
	v_mov_b32_e32 v146, v24
	v_mov_b32_e32 v147, v24
	v_mov_b32_e32 v148, v24
	v_mov_b32_e32 v149, v24
	v_mov_b32_e32 v150, v24
	v_mov_b32_e32 v151, v24
	s_waitcnt lgkmcnt(0)
	s_barrier

; #define G_LOAD(kt_) do { \
;     if constexpr (AF32) { _Pragma("unroll") for (int i = 0; i < 4; ++i) ld16_sc1(ra[i], Af + (size_t)i * 32 * lda + (kt_) * 32); } \
;     else { _Pragma("unroll") for (int i = 0; i < 2; ++i) ld16_sc1(rab[i], Ab + (size_t)i * 64 * lda + (kt_) * 32); } \
;     _Pragma("unroll") for (int i = 0; i < 4; ++i) ld16_sc1(rb[i], Bp + (size_t)(kt_) * bstep + i * 2048); } while (0)
; template <bool AF32, class Epi>
; __device__ __forceinline__ void gemm_tile(unsigned char* smem, const void* Ap, int lda, const bf16_t* WT, int N, int K, const Epi& epi, int m0, int n0,
;                                           GPre& pr, bool preloaded, const void* nAp, int nn0, bool has_next) {
;     ...
;   const float* Af = (const float*)Ap + (size_t)(tid >> 3) * lda + (tid & 7) * 4;
;   const bf16_t* Ab = (const bf16_t*)Ap + (size_t)(tid >> 2) * lda + (tid & 3) * 8;
;   const bf16_t* Bp = WT + (size_t)n0 * 32 + tid * 8;
;   const size_t bstep = (size_t)N * 32;
;   const int awf = (tid >> 3) * GLD + (tid & 7) * 4;
;   const int awb = (tid >> 2) * GLD + (tid & 3) * 8;
;     ...
;   if (!preloaded) G_LOAD(0);
;   G_STORE(0);
;   if (nk > 1) G_LOAD(1);
;   __syncthreads();
;   for (int kt = 0; kt < nk; ++kt) {
;     const int cur = kt & 1;
;     if (kt + 1 < nk) G_STORE(cur ^ 1);
;     if (kt + 2 < nk) G_LOAD(kt + 2);
;     const bf16_t* a_s = sbase + cur * G_STAGE + (wr * 64 + l15) * GLD + quad * 8;
;     const bf16_t* b_s = sbase + cur * G_STAGE + 128 * GLD + (wc * 128 + l15) * GLD + quad * 8;
.LBB0_677:
	v_lshlrev_b64 v[186:187], 10, v[178:179]
	v_and_b32_e32 v52, 15, v34
	v_bfe_u32 v179, v34, 4, 2
	v_lshrrev_b32_e32 v35, 2, v34
	v_and_b32_e32 v34, 24, v182
	s_waitcnt vmcnt(0)
	v_mad_u64_u32 v[162:163], s[66:67], v35, 40, v[34:35]
	v_lshrrev_b32_e32 v250, 2, v210
	v_add_u32_e32 v251, 4, v250
	v_and_b32_e32 v251, 8, v251
	v_and_b32_e32 v252, 3, v210
	v_lshlrev_b32_e32 v252, 3, v252
	v_xor_b32_e32 v252, v252, v251
	v_mad_u32_u24 v162, v250, 40, v252
	v_cvt_pk_bf16_f32 v34, v24, v25
	v_mov_b32_e32 v37, v24
	v_mov_b32_e32 v24, v29
	v_mov_b32_e32 v36, v28
	v_pk_mul_f32 v[24:25], v[24:25], v[24:25]
	v_lshlrev_b32_e32 v188, 2, v191
	v_pk_fma_f32 v[24:25], v[36:37], v[36:37], v[24:25]
	v_mov_b32_e32 v36, v30
	v_mov_b32_e32 v37, v26
	v_mad_u64_u32 v[160:161], s[66:67], v178, 40, v[188:189]
	v_lshrrev_b32_e32 v250, 3, v210
	v_add_u32_e32 v251, 4, v250
	v_and_b32_e32 v251, 8, v251
	v_and_b32_e32 v252, 7, v210
	v_lshlrev_b32_e32 v252, 2, v252
	v_xor_b32_e32 v252, v252, v251
	v_mad_u32_u24 v160, v250, 40, v252
	v_cvt_pk_bf16_f32 v35, v26, v27
	v_pk_fma_f32 v[24:25], v[36:37], v[36:37], v[24:25]
	v_mov_b32_e32 v26, v31
	v_lshlrev_b32_e32 v161, 1, v160
	v_pk_fma_f32 v[184:185], v[26:27], v[26:27], v[24:25]
	v_cvt_pk_bf16_f32 v24, v28, v29
	v_cvt_pk_bf16_f32 v25, v30, v31
	ds_write2st64_b64 v161, v[34:35], v[24:25] offset1:5
	v_cvt_pk_bf16_f32 v24, v16, v17
	v_mov_b32_e32 v27, v16
	v_mov_b32_e32 v16, v21
	v_mov_b32_e32 v26, v20
	v_pk_mul_f32 v[16:17], v[16:17], v[16:17]
	v_cvt_pk_bf16_f32 v25, v18, v19
	v_pk_fma_f32 v[16:17], v[26:27], v[26:27], v[16:17]
	v_mov_b32_e32 v26, v22
	v_mov_b32_e32 v27, v18
	v_pk_fma_f32 v[16:17], v[26:27], v[26:27], v[16:17]
	v_mov_b32_e32 v18, v23
	v_pk_fma_f32 v[180:181], v[18:19], v[18:19], v[16:17]
	v_cvt_pk_bf16_f32 v16, v20, v21
	v_cvt_pk_bf16_f32 v17, v22, v23
	v_lshlrev_b32_e32 v163, 1, v162
	ds_write2st64_b64 v161, v[24:25], v[16:17] offset0:10 offset1:15
	ds_write_b128 v163, v[0:3] offset:10240
	ds_write_b128 v163, v[4:7] offset:15360
	ds_write_b128 v163, v[8:11] offset:20480
	ds_write_b128 v163, v[12:15] offset:25600
	v_lshl_add_u64 v[0:1], v[32:33], 0, s[26:27]
	global_load_dwordx4 v[44:47], v[0:1], off sc1
	v_lshl_add_u64 v[0:1], v[32:33], 0, s[28:29]
	global_load_dwordx4 v[40:43], v[0:1], off sc1
	v_lshl_add_u64 v[0:1], v[32:33], 0, s[30:31]
	s_ashr_i32 s3, s47, 1
	global_load_dwordx4 v[36:39], v[0:1], off sc1
	v_lshl_add_u64 v[0:1], v[32:33], 0, s[34:35]
	s_andn2_b32 s3, s3, 63
	global_load_dwordx4 v[32:35], v[0:1], off sc1
	v_lshl_add_u64 v[0:1], v[50:51], 0, s[36:37]
	v_or_b32_e32 v192, s3, v52
	s_lshl_b32 s3, s47, 1
	global_load_dwordx4 v[0:3], v[0:1], off sc1
	v_lshl_add_u64 v[4:5], v[50:51], 0, s[38:39]
	s_and_b32 s3, s3, 0x80
	global_load_dwordx4 v[4:7], v[4:5], off sc1
	v_lshl_add_u64 v[8:9], v[50:51], 0, s[40:41]
	v_or_b32_e32 v16, s3, v52
	global_load_dwordx4 v[8:11], v[8:9], off sc1
	v_lshl_add_u64 v[12:13], v[50:51], 0, s[42:43]
	v_mul_u32_u24_e32 v168, 0x50, v16
	v_lshl_add_u64 v[16:17], s[50:51], 0, v[48:49]
	global_load_dwordx4 v[12:15], v[12:13], off sc1
	s_add_u32 s52, s58, s52
	v_lshl_add_u64 v[16:17], v[16:17], 0, v[176:177]
	v_lshlrev_b32_e32 v18, 3, v179
	s_addc_u32 s53, s59, s53
	v_lshl_add_u64 v[166:167], s[12:13], 0, v[16:17]
	v_mov_b32_e32 v16, 0
	v_mul_lo_u32 v169, v192, s60
	v_lshl_add_u64 v[164:165], v[182:183], 1, s[52:53]
	s_mov_b32 s49, 0
	v_lshlrev_b32_e32 v170, 1, v18
	v_add_u32_e32 v250, 4, v210
	v_and_b32_e32 v250, 8, v250
	v_lshlrev_b32_e32 v250, 1, v250
	v_xor_b32_e32 v170, v170, v250
	v_mov_b32_e32 v17, v16
	v_mov_b32_e32 v18, v16
	v_mov_b32_e32 v19, v16
	v_mov_b32_e32 v20, v16
	v_mov_b32_e32 v21, v16
	v_mov_b32_e32 v22, v16
	v_mov_b32_e32 v23, v16
	v_mov_b32_e32 v24, v16
	v_mov_b32_e32 v25, v16
	v_mov_b32_e32 v26, v16
	v_mov_b32_e32 v27, v16
	v_mov_b32_e32 v28, v16
	v_mov_b32_e32 v29, v16
	v_mov_b32_e32 v30, v16
	v_mov_b32_e32 v31, v16
	v_mov_b32_e32 v52, v16
	v_mov_b32_e32 v53, v16
	v_mov_b32_e32 v54, v16
	v_mov_b32_e32 v55, v16
	v_mov_b32_e32 v60, v16
	v_mov_b32_e32 v61, v16
	v_mov_b32_e32 v62, v16
	v_mov_b32_e32 v63, v16
	v_mov_b32_e32 v68, v16
	v_mov_b32_e32 v69, v16
	v_mov_b32_e32 v70, v16
	v_mov_b32_e32 v71, v16
	v_mov_b32_e32 v76, v16
	v_mov_b32_e32 v77, v16
	v_mov_b32_e32 v78, v16
	v_mov_b32_e32 v79, v16
	v_mov_b32_e32 v48, v16
	v_mov_b32_e32 v49, v16
	v_mov_b32_e32 v50, v16
	v_mov_b32_e32 v51, v16
	v_mov_b32_e32 v56, v16
	v_mov_b32_e32 v57, v16
	v_mov_b32_e32 v58, v16
	v_mov_b32_e32 v59, v16
	v_mov_b32_e32 v64, v16
	v_mov_b32_e32 v65, v16
	v_mov_b32_e32 v66, v16
	v_mov_b32_e32 v67, v16
	v_mov_b32_e32 v72, v16
	v_mov_b32_e32 v73, v16
	v_mov_b32_e32 v74, v16
	v_mov_b32_e32 v75, v16
	v_mov_b32_e32 v84, v16
	v_mov_b32_e32 v85, v16
	v_mov_b32_e32 v86, v16
	v_mov_b32_e32 v87, v16
	v_mov_b32_e32 v92, v16
	v_mov_b32_e32 v93, v16
	v_mov_b32_e32 v94, v16
	v_mov_b32_e32 v95, v16
	v_mov_b32_e32 v100, v16
	v_mov_b32_e32 v101, v16
	v_mov_b32_e32 v102, v16
	v_mov_b32_e32 v103, v16
	v_mov_b32_e32 v108, v16
	v_mov_b32_e32 v109, v16
	v_mov_b32_e32 v110, v16
	v_mov_b32_e32 v111, v16
	v_mov_b32_e32 v80, v16
	v_mov_b32_e32 v81, v16
	v_mov_b32_e32 v82, v16
	v_mov_b32_e32 v83, v16
	v_mov_b32_e32 v88, v16
	v_mov_b32_e32 v89, v16
	v_mov_b32_e32 v90, v16
	v_mov_b32_e32 v91, v16
	v_mov_b32_e32 v96, v16
	v_mov_b32_e32 v97, v16
	v_mov_b32_e32 v98, v16
	v_mov_b32_e32 v99, v16
	v_mov_b32_e32 v104, v16
	v_mov_b32_e32 v105, v16
	v_mov_b32_e32 v106, v16
	v_mov_b32_e32 v107, v16
	v_mov_b32_e32 v116, v16
	v_mov_b32_e32 v117, v16
	v_mov_b32_e32 v118, v16
	v_mov_b32_e32 v119, v16
	v_mov_b32_e32 v124, v16
	v_mov_b32_e32 v125, v16
	v_mov_b32_e32 v126, v16
	v_mov_b32_e32 v127, v16
	v_mov_b32_e32 v136, v16
	v_mov_b32_e32 v137, v16
	v_mov_b32_e32 v138, v16
	v_mov_b32_e32 v139, v16
	v_mov_b32_e32 v140, v16
	v_mov_b32_e32 v141, v16
	v_mov_b32_e32 v142, v16
	v_mov_b32_e32 v143, v16
	v_mov_b32_e32 v112, v16
	v_mov_b32_e32 v113, v16
	v_mov_b32_e32 v114, v16
	v_mov_b32_e32 v115, v16
	v_mov_b32_e32 v120, v16
	v_mov_b32_e32 v121, v16
	v_mov_b32_e32 v122, v16
	v_mov_b32_e32 v123, v16
	v_mov_b32_e32 v128, v16
	v_mov_b32_e32 v129, v16
	v_mov_b32_e32 v130, v16
	v_mov_b32_e32 v131, v16
	v_mov_b32_e32 v132, v16
	v_mov_b32_e32 v133, v16
	v_mov_b32_e32 v134, v16
	v_mov_b32_e32 v135, v16
	v_mov_b32_e32 v144, v16
	v_mov_b32_e32 v145, v16
	v_mov_b32_e32 v146, v16
	v_mov_b32_e32 v147, v16
	v_mov_b32_e32 v148, v16
	v_mov_b32_e32 v149, v16
	v_mov_b32_e32 v150, v16
	v_mov_b32_e32 v151, v16
	v_mov_b32_e32 v152, v16
	v_mov_b32_e32 v153, v16
	v_mov_b32_e32 v154, v16
	v_mov_b32_e32 v155, v16
	v_mov_b32_e32 v156, v16
	v_mov_b32_e32 v157, v16
	v_mov_b32_e32 v158, v16
	v_mov_b32_e32 v159, v16
	s_waitcnt lgkmcnt(0)
	s_barrier
